# dense attention: v_pk_add_f32 row-sum accumulation split into scalar v_add_f32 pairs, bit-identical
# speedup vs baseline: 1.0084x; 1.0035x over previous
; #define RAW_BARRIER() do { asm volatile("s_waitcnt lgkmcnt(0)" ::: "memory"); __builtin_amdgcn_s_barrier(); } while (0)
; template <int DK, int QB, bool NA>
; DEVI void attn_item(const AttnArgs& a, unsigned char* smem) {
;     ...
;   bf16x8 qf[QB][KS];
; #pragma unroll
;   for (int qb = 0; qb < QB; ++qb) {
;     const bf16_t* qp = a.Q + (size_t)((wact ? w * QB * 16 : 0) + qb * 16 + l16) * a.ldq + g * 8;
; #pragma unroll
;     for (int ks = 0; ks < KS; ++ks) qf[qb][ks] = *(const bf16x8*)(qp + ks * 32);
;   }
;   float m[QB], l[QB];
;   f32x4 o[4][QB];
; #pragma unroll
;   for (int qb = 0; qb < QB; ++qb) {
;     m[qb] = NA ? -1e30f : 0.f; l[qb] = 0.f;
; #pragma unroll
;     for (int db = 0; db < 4; ++db) o[db][qb] = (f32x4){0.f, 0.f, 0.f, 0.f};
;   }
;   const int r8 = tid >> 3, c8 = (tid & 7) ^ ((tid >> 4) & 7);
;   const bf16_t* Kn = a.K + (size_t)r8 * a.ldk + c8 * 8;
;   const bf16_t* Kr = a.K + (size_t)(tid >> 2) * a.ldk + 64 + (((tid & 3) ^ ((0 - (tid >> 4)) & 3)) * 8);
;   const bf16_t* Vg = a.Vt + (size_t)r8 * a.Lk + c8 * 8;
;   const size_t kstep = (size_t)32 * a.ldk, vstep = (size_t)32 * a.Lk;
;   unsigned char* lds_t = smem + tid * 16;
;     ...
;   asm volatile("s_waitcnt vmcnt(0)" ::: "memory");
;   RAW_BARRIER();
;   ATT_ISSUE(0, 0);
;   if (nt > 1) ATT_ISSUE(1, 1);
;   const int sw8 = (l16 >> 1) & 7, vsw = sw8 << 1;
;   const unsigned ka0 = l16 * 128 + ((g ^ sw8) << 4), ka1 = l16 * 128 + (((4 + g) ^ sw8) << 4);
;   const unsigned kr = 8192 + l16 * 64 + ((g ^ ((0 - (l16 >> 2)) & 3)) << 4);
;   const unsigned vb00 = 12288 + l16 * 128 + (((0 + g) ^ vsw) << 3), vb01 = 12288 + l16 * 128 + (((4 + g) ^ vsw) << 3);
;   const unsigned vb10 = 12288 + l16 * 128 + (((8 + g) ^ vsw) << 3), vb11 = 12288 + l16 * 128 + (((12 + g) ^ vsw) << 3);
;   const unsigned biasA = lbase + ATT_BIAS_OFF;
;   const int qc = w * 16 + l16;
;   const int cs0 = min(max(qc - 8, 0), 48);
;   int cs = 0, is = 2;
; DEVI void attn_dense_phase(const Params& p, unsigned char* smem, unsigned* ctr) {
;     ...
;       const int hq = h16 - 8, kvh = hq >> 2;
;       a.Q = Hb + H_PROJ + (size_t)q0 * 1056 + 384 + hq * 64; a.ldq = 1056;
;       a.K = Hb + H_PROJ + (size_t)kb * 1056 + 896 + kvh * 64; a.ldk = 1056;
;       a.Vt = Hb + H_VTG + (size_t)128 * kb + (size_t)(kvh * 64) * Lk;
;       a.sc2 = 0.125f * LOG2E;
.LBB0_2263:
	s_or_b32 s62, s60, 64
	s_lshl_b32 s0, s8, 7
	s_cmp_lt_i32 s8, 0
	s_cselect_b32 s0, s60, s0
	s_add_i32 s59, s2, s0
	s_lshr_b32 s61, s60, 6
	s_lshl_b32 s56, s58, 6
	s_cmp_gt_u32 s58, 7
	s_cbranch_scc0 .LBB0_2289
	s_add_i32 s0, s58, -8
	s_mul_i32 s3, s59, 0x840
	v_readlane_b32 s28, v251, 52
	s_mul_hi_i32 s1, s59, 0x840
	s_add_u32 s3, s28, s3
	v_readlane_b32 s29, v251, 53
	s_addc_u32 s1, s29, s1
	s_lshl_b32 s8, s0, 7
	s_add_u32 s8, s3, s8
	s_addc_u32 s9, s1, 0
	s_ashr_i32 s3, s2, 31
	s_mul_i32 s20, s2, 0x840
	s_mul_hi_i32 s1, s2, 0x840
	s_add_u32 s20, s28, s20
	s_addc_u32 s1, s29, s1
	s_lshl_b32 s0, s0, 4
	s_and_b32 s42, s0, 0x7fffffc0
	s_lshl_b32 s0, s42, 1
	s_add_u32 s40, s20, s0
	s_addc_u32 s41, s1, 0
	s_lshl_b64 s[0:1], s[2:3], 8
	v_readlane_b32 s3, v251, 56
	s_add_u32 s3, s3, s0
	v_readlane_b32 s0, v251, 57
	s_addc_u32 s20, s0, s1
	s_mul_hi_u32 s1, s62, s42
	s_mul_i32 s0, s62, s42
	v_mov_b32_e32 v3, v177
	s_lshl_b64 s[0:1], s[0:1], 1
	s_add_u32 s42, s3, s0
	v_ashrrev_i32_e32 v0, 1, v3
	v_and_b32_e32 v128, 0xffffffe0, v0
	s_addc_u32 s43, s20, s1
	v_cmp_gt_i32_e64 s[0:1], s57, v128
	v_and_b32_e32 v126, 15, v3
	v_bfe_u32 v127, v3, 4, 2
	v_cndmask_b32_e64 v0, 0, v128, s[0:1]
	v_or_b32_e32 v12, v0, v126
	v_lshlrev_b32_e32 v0, 4, v127
	v_lshrrev_b32_e32 v2, 4, v3
	v_lshl_add_u64 v[4:5], s[8:9], 0, v[0:1]
	s_movk_i32 s3, 0x840
	v_or_b32_e32 v0, 16, v12
	v_mad_i64_i32 v[6:7], s[8:9], v12, s3, v[4:5]
	v_mad_i64_i32 v[4:5], s[8:9], v0, s3, v[4:5]
	v_xor_b32_e32 v0, v2, v3
	v_ashrrev_i32_e32 v22, 3, v3
	v_mov_b64_e32 v[20:21], s[40:41]
	v_lshlrev_b32_e32 v0, 4, v0
	v_mad_i64_i32 v[20:21], s[8:9], v22, s3, v[20:21]
	v_and_b32_e32 v0, 0x70, v0
	v_lshl_add_u64 v[106:107], v[20:21], 0, v[0:1]
	s_mov_b64 s[8:9], 0x700
	v_lshl_add_u64 v[20:21], v[106:107], 0, s[8:9]
	v_mad_i64_i32 v[22:23], s[8:9], v22, s62, 0
	v_lshl_add_u64 v[22:23], v[22:23], 1, s[42:43]
	v_lshlrev_b32_e32 v185, 4, v3
	v_lshl_add_u64 v[104:105], v[22:23], 0, v[0:1]
	v_readfirstlane_b32 s3, v185
	v_add_u32_e32 v0, 0x1000, v185
	global_load_dwordx4 v[16:19], v[6:7], off offset:768
	global_load_dwordx4 v[8:11], v[6:7], off offset:832
	global_load_dwordx4 v[12:15], v[4:5], off offset:768
	s_nop 0
	global_load_dwordx4 v[4:7], v[4:5], off offset:832
	s_waitcnt vmcnt(0)
	s_mov_b32 m0, s3
	s_mov_b64 s[8:9], 0x10f00
	v_readfirstlane_b32 s3, v0
	v_add_u32_e32 v0, 0x3000, v185
	s_waitcnt lgkmcnt(0)
	s_barrier
	global_load_lds_dwordx4 v[20:21], off
	v_lshl_add_u64 v[20:21], v[106:107], 0, s[8:9]
	s_mov_b32 m0, s3
	v_readfirstlane_b32 s3, v0
	v_add_u32_e32 v0, 0x4000, v185
	global_load_lds_dwordx4 v[20:21], off
	s_mov_b32 m0, s3
	s_lshl_b32 s20, s62, 6
	v_readfirstlane_b32 s3, v0
	v_add_u32_e32 v0, 0x5000, v185
	global_load_lds_dwordx4 v[104:105], off
	v_lshl_add_u64 v[108:109], v[104:105], 0, s[20:21]
	s_mov_b32 m0, s3
	s_mov_b64 s[8:9], 0x21700
	v_readfirstlane_b32 s3, v0
	v_add_u32_e32 v0, 0x6000, v185
	global_load_lds_dwordx4 v[108:109], off
	v_lshl_add_u64 v[20:21], v[106:107], 0, s[8:9]
	s_mov_b32 m0, s3
	s_mov_b64 s[8:9], 0x31f00
	v_readfirstlane_b32 s3, v0
	v_add_u32_e32 v0, 0x8000, v185
	global_load_lds_dwordx4 v[20:21], off
	v_lshl_add_u64 v[20:21], v[106:107], 0, s[8:9]
	s_mov_b32 m0, s3
	s_mov_b64 s[8:9], 0x80
	v_readfirstlane_b32 s3, v0
	v_add_u32_e32 v0, 0x9000, v185
	global_load_lds_dwordx4 v[20:21], off
	v_lshl_add_u64 v[20:21], v[104:105], 0, s[8:9]
	s_mov_b32 m0, s3
	v_readfirstlane_b32 s3, v0
	global_load_lds_dwordx4 v[20:21], off
	v_lshl_add_u64 v[20:21], v[108:109], 0, s[8:9]
	s_mov_b32 m0, s3
	v_add_u32_e32 v0, 0xa000, v185
	global_load_lds_dwordx4 v[20:21], off
	s_mov_b64 s[8:9], 0x42700
	v_readfirstlane_b32 s3, v0
	v_add_u32_e32 v0, 0xb000, v185
	s_waitcnt vmcnt(4)
	v_lshl_add_u64 v[20:21], v[106:107], 0, s[8:9]
	s_mov_b32 m0, s3
	s_mov_b64 s[8:9], 0x52f00
	v_readfirstlane_b32 s3, v0
	v_add_u32_e32 v0, 0xd000, v185
	s_waitcnt lgkmcnt(0)
	s_barrier
	global_load_lds_dwordx4 v[20:21], off
	v_lshl_add_u64 v[20:21], v[106:107], 0, s[8:9]
	s_mov_b32 m0, s3
	s_mov_b64 s[8:9], 0x100
	v_readfirstlane_b32 s3, v0
	v_add_u32_e32 v0, 0xe000, v185
	global_load_lds_dwordx4 v[20:21], off
	v_lshl_add_u64 v[20:21], v[104:105], 0, s[8:9]
	s_mov_b32 m0, s3
	v_readfirstlane_b32 s3, v0
	global_load_lds_dwordx4 v[20:21], off
	v_lshl_add_u64 v[20:21], v[108:109], 0, s[8:9]
	s_mov_b32 m0, s3
	v_cmp_le_i32_e32 vcc, s57, v128
	global_load_lds_dwordx4 v[20:21], off
	s_and_saveexec_b64 s[8:9], vcc
	s_xor_b64 s[8:9], exec, s[8:9]
	s_or_saveexec_b64 s[42:43], s[8:9]
	v_bfe_u32 v0, v3, 1, 3
	v_lshlrev_b32_e32 v3, 1, v0
	v_lshlrev_b32_e32 v20, 7, v126
	v_bitop3_b32 v21, v2, v0, 3 bitop3:0x6c
	v_bitop3_b32 v0, v127, v0, 4 bitop3:0x36
	v_lshl_or_b32 v184, v0, 4, v20
	v_or_b32_e32 v0, 0x3000, v20
	v_bitop3_b32 v2, v3, v2, 3 bitop3:0x78
	v_lshl_or_b32 v129, v2, 3, v0
	v_bitop3_b32 v2, v127, v3, 4 bitop3:0x36
	v_lshl_or_b32 v180, v2, 3, v0
	v_bitop3_b32 v2, v127, v3, 8 bitop3:0x36
	v_lshl_or_b32 v181, v2, 3, v0
	v_bitop3_b32 v2, v127, v3, 12 bitop3:0x36
	v_lshl_or_b32 v182, v2, 3, v0
	v_mov_b32_e32 v2, v1
	v_mov_b32_e32 v3, v1
	v_lshl_or_b32 v183, v21, 4, v20
	v_mov_b32_e32 v0, v1
	v_mov_b64_e32 v[22:23], v[2:3]
	v_mov_b64_e32 v[26:27], v[2:3]
	v_mov_b64_e32 v[30:31], v[2:3]
	v_mov_b64_e32 v[34:35], v[2:3]
	v_mov_b64_e32 v[38:39], v[2:3]
	v_mov_b64_e32 v[42:43], v[2:3]
	v_mov_b64_e32 v[46:47], v[2:3]
	v_mov_b64_e32 v[50:51], v[2:3]
	s_mov_b32 s8, 0
	v_mov_b32_e32 v100, 0
	v_mov_b64_e32 v[20:21], v[0:1]
	v_mov_b64_e32 v[24:25], v[0:1]
	v_mov_b64_e32 v[28:29], v[0:1]
	v_mov_b64_e32 v[32:33], v[0:1]
	v_mov_b64_e32 v[36:37], v[0:1]
	v_mov_b64_e32 v[40:41], v[0:1]
	v_mov_b64_e32 v[44:45], v[0:1]
	v_mov_b64_e32 v[48:49], v[0:1]
	v_mov_b32_e32 v101, 0
	v_mov_b32_e32 v102, 0
	v_mov_b32_e32 v103, 0
	s_xor_b64 exec, exec, s[42:43]
	s_cbranch_execz .LBB0_2266
; template <int DK, int QB, bool NA>
; DEVI void attn_item(const AttnArgs& a, unsigned char* smem) {
;     ...
;         const unsigned a0 = cur + ka0, a1 = cur + ka1, a2 = cur + kr;
;         k0[0] = ldsr<0>(a0); k0[1] = ldsr<2048>(a0); k0[2] = ldsr<4096>(a0); k0[3] = ldsr<6144>(a0);
;         k1[0] = ldsr<0>(a1); k1[1] = ldsr<2048>(a1); k1[2] = ldsr<4096>(a1); k1[3] = ldsr<6144>(a1);
;         if constexpr (KS == 3) { k2[0] = ldsr<0>(a2); k2[1] = ldsr<1024>(a2); k2[2] = ldsr<2048>(a2); k2[3] = ldsr<3072>(a2); }
;         if constexpr (KS == 3) asm volatile("s_waitcnt lgkmcnt(8)" : "+v"(k0[0]), "+v"(k0[1]), "+v"(k0[2]), "+v"(k0[3]) :: "memory");
;         else                   asm volatile("s_waitcnt lgkmcnt(4)" : "+v"(k0[0]), "+v"(k0[1]), "+v"(k0[2]), "+v"(k0[3]) :: "memory");
;         __builtin_amdgcn_sched_barrier(0);
; #pragma unroll
;         for (int kb = 0; kb < 4; ++kb)
; #pragma unroll
;           for (int qb = 0; qb < QB; ++qb) s[kb][qb] = __builtin_amdgcn_mfma_f32_16x16x32_bf16(k0[kb], qf[qb][0], s[kb][qb], 0, 0, 0);
;         if constexpr (KS == 3) asm volatile("s_waitcnt lgkmcnt(4)" : "+v"(k1[0]), "+v"(k1[1]), "+v"(k1[2]), "+v"(k1[3]) :: "memory");
;         else                   asm volatile("s_waitcnt lgkmcnt(0)" : "+v"(k1[0]), "+v"(k1[1]), "+v"(k1[2]), "+v"(k1[3]) :: "memory");
;         __builtin_amdgcn_sched_barrier(0);
; #pragma unroll
;         for (int kb = 0; kb < 4; ++kb)
; #pragma unroll
;           for (int qb = 0; qb < QB; ++qb) s[kb][qb] = __builtin_amdgcn_mfma_f32_16x16x32_bf16(k1[kb], qf[qb][1], s[kb][qb], 0, 0, 0);
;     ...
;           const f32x2 scv = {a.sc2, a.sc2}, nmv = {-m[qb], -m[qb]};
;           f32x2 t[4][2];
; #pragma unroll
;           for (int kb = 0; kb < 4; ++kb)
; #pragma unroll
;             for (int h = 0; h < 2; ++h) {
;               const f32x2 sv = {s[kb][qb][2 * h], s[kb][qb][2 * h + 1]};
;               t[kb][h] = sv * scv + nmv;
;             }
;           float mx = fmaxf(t[0][0].x, t[0][0].y);
; #pragma unroll
;           for (int kb = 0; kb < 4; ++kb)
; #pragma unroll
;             for (int h = 0; h < 2; ++h) mx = fmaxf(mx, fmaxf(t[kb][h].x, t[kb][h].y));
;           if (j == 0 || __any(mx > 6.f)) {
;             mx = xmax32(xmax16(mx));
;             const float d = (j == 0) ? mx : fmaxf(mx, 0.f);
;             const float alpha = __builtin_amdgcn_exp2f(-d);
;             const f32x2 dv = {d, d};
; #pragma unroll
	ds_read_b128 v[20:23], v183 offset:0
	ds_read_b128 v[24:27], v183 offset:0x800
	ds_read_b128 v[28:31], v183 offset:0x1000
	ds_read_b128 v[32:35], v183 offset:0x1800
	ds_read_b128 v[36:39], v184 offset:0
	ds_read_b128 v[40:43], v184 offset:0x800
	ds_read_b128 v[44:47], v184 offset:0x1000
	ds_read_b128 v[48:51], v184 offset:0x1800
	s_nop 0
	s_waitcnt lgkmcnt(4)
	s_waitcnt vmcnt(0)
	s_setprio 1
	v_mfma_f32_16x16x32_bf16 v[52:55], v[20:23], v[16:19], 0
	s_waitcnt lgkmcnt(0)
	v_mfma_f32_16x16x32_bf16 v[20:23], v[20:23], v[12:15], 0
	v_mfma_f32_16x16x32_bf16 v[56:59], v[24:27], v[16:19], 0
	v_mfma_f32_16x16x32_bf16 v[24:27], v[24:27], v[12:15], 0
	v_mfma_f32_16x16x32_bf16 v[68:71], v[28:31], v[16:19], 0
	v_mfma_f32_16x16x32_bf16 v[28:31], v[28:31], v[12:15], 0
	v_mfma_f32_16x16x32_bf16 v[72:75], v[32:35], v[16:19], 0
	v_mfma_f32_16x16x32_bf16 v[32:35], v[32:35], v[12:15], 0
	v_mfma_f32_16x16x32_bf16 v[52:55], v[36:39], v[8:11], v[52:55]
	v_mfma_f32_16x16x32_bf16 v[56:59], v[40:43], v[8:11], v[56:59]
	v_mfma_f32_16x16x32_bf16 v[76:79], v[44:47], v[8:11], v[68:71]
	s_nop 5
	v_mul_f32_e64 v84, v54, s92
	v_mul_f32_e64 v85, v55, s92
	v_pk_mul_f32 v[2:3], v[52:53], s[92:93] op_sel_hi:[1,0]
	v_max_f32_e32 v0, v84, v85
	v_max3_f32 v0, v2, v3, v0
	v_pk_mul_f32 v[2:3], v[56:57], s[92:93] op_sel_hi:[1,0]
	v_mfma_f32_16x16x32_bf16 v[80:83], v[48:51], v[8:11], v[72:75]
	v_max_f32_e32 v84, v2, v3
	v_pk_mul_f32 v[2:3], v[58:59], s[92:93] op_sel_hi:[1,0]
	s_nop 0
	v_max_f32_e32 v2, v2, v3
	v_max3_f32 v0, v0, v84, v2
	v_pk_mul_f32 v[2:3], v[76:77], s[92:93] op_sel_hi:[1,0]
	v_mfma_f32_16x16x32_bf16 v[60:63], v[36:39], v[4:7], v[20:23]
	v_max_f32_e32 v84, v2, v3
	v_pk_mul_f32 v[2:3], v[78:79], s[92:93] op_sel_hi:[1,0]
	s_nop 0
	v_max_f32_e32 v2, v2, v3
	v_max3_f32 v0, v0, v84, v2
	v_pk_mul_f32 v[2:3], v[80:81], s[92:93] op_sel_hi:[1,0]
	v_mfma_f32_16x16x32_bf16 v[64:67], v[40:43], v[4:7], v[24:27]
	s_setprio 0
	v_max_f32_e32 v84, v2, v3
	v_pk_mul_f32 v[2:3], v[82:83], s[92:93] op_sel_hi:[1,0]
	s_nop 0
	v_max_f32_e32 v2, v2, v3
	v_max3_f32 v0, v0, v84, v2
	v_mov_b32_e32 v2, v0
	s_nop 1
	v_permlane16_swap_b32_e32 v0, v2
	v_max_f32_e32 v2, v2, v2
	v_max_f32_e32 v0, v0, v0
	v_max_f32_e32 v0, v0, v2
	v_mov_b32_e32 v2, v0
	s_nop 1
	v_permlane32_swap_b32_e32 v0, v2
	v_max_f32_e32 v2, v2, v2
	v_max_f32_e32 v0, v0, v0
	v_max_f32_e32 v84, v0, v2
	v_fma_f32 v52, v52, s92, -v84
	v_fma_f32 v53, v53, s92, -v84
	v_fma_f32 v54, v54, s92, -v84
	v_fma_f32 v55, v55, s92, -v84
	v_exp_f32_e32 v52, v52
	v_exp_f32_e32 v53, v53
	v_exp_f32_e32 v54, v54
	v_exp_f32_e32 v55, v55
	v_fma_f32 v56, v56, s92, -v84
	v_fma_f32 v57, v57, s92, -v84
	v_add_f32_e32 v86, 0, v52
	v_add_f32_e32 v87, 0, v53
	v_fma_f32 v58, v58, s92, -v84
	v_fma_f32 v59, v59, s92, -v84
	v_cvt_pk_bf16_f32 v52, v52, v53
	v_add_f32_e32 v86, v54, v86
	v_add_f32_e32 v87, v55, v87
	v_cvt_pk_bf16_f32 v53, v54, v55
	v_exp_f32_e32 v54, v56
	v_exp_f32_e32 v55, v57
	v_exp_f32_e32 v58, v58
	v_exp_f32_e32 v59, v59
	v_fma_f32 v76, v76, s92, -v84
	v_fma_f32 v77, v77, s92, -v84
	v_add_f32_e32 v56, v54, v86
	v_add_f32_e32 v57, v55, v87
	v_cvt_pk_bf16_f32 v54, v54, v55
	v_add_f32_e32 v56, v58, v56
	v_add_f32_e32 v57, v59, v57
	v_cvt_pk_bf16_f32 v55, v58, v59
	v_exp_f32_e32 v58, v76
	v_exp_f32_e32 v59, v77
	v_fma_f32 v78, v78, s92, -v84
	v_fma_f32 v79, v79, s92, -v84
	v_fma_f32 v80, v80, s92, -v84
	v_fma_f32 v81, v81, s92, -v84
	v_fma_f32 v82, v82, s92, -v84
	v_fma_f32 v83, v83, s92, -v84
	v_add_f32_e32 v76, v58, v56
	v_add_f32_e32 v77, v59, v57
	v_cvt_pk_bf16_f32 v56, v58, v59
	v_exp_f32_e32 v58, v78
	v_exp_f32_e32 v59, v79
	v_exp_f32_e32 v78, v82
	v_exp_f32_e32 v79, v83
	s_setprio 1
	v_mfma_f32_16x16x32_bf16 v[68:71], v[44:47], v[4:7], v[28:31]
	v_add_f32_e64 v76, v58, v76
	v_add_f32_e64 v77, v59, v77
	v_cvt_pk_bf16_f32 v57, v58, v59
	v_exp_f32_e32 v58, v80
	v_exp_f32_e32 v59, v81
	v_pk_mul_f32 v[80:81], v[62:63], s[92:93] op_sel_hi:[1,0]
	v_mfma_f32_16x16x32_bf16 v[72:75], v[48:51], v[4:7], v[32:35]
	s_setprio 0
	v_max_f32_e32 v0, v80, v81
	v_add_f32_e32 v76, v58, v76
	v_add_f32_e32 v77, v59, v77
	v_cvt_pk_bf16_f32 v58, v58, v59
	v_add_f32_e32 v76, v78, v76
	v_add_f32_e32 v77, v79, v77
	v_cvt_pk_bf16_f32 v59, v78, v79
	v_pk_mul_f32 v[78:79], v[60:61], s[92:93] op_sel_hi:[1,0]
	v_exp_f32_e64 v3, -v84
	v_max3_f32 v0, v78, v79, v0
	v_pk_mul_f32 v[78:79], v[64:65], s[92:93] op_sel_hi:[1,0]
	ds_read_b64 v[48:49], v129 offset:0
	ds_read_b64 v[50:51], v180 offset:0
	ds_read_b64 v[44:45], v129 offset:0x800
	ds_read_b64 v[46:47], v180 offset:0x800
	ds_read_b64 v[40:41], v129 offset:0x1000
	s_nop 0
	v_max_f32_e32 v2, v78, v79
	v_pk_mul_f32 v[78:79], v[66:67], s[92:93] op_sel_hi:[1,0]
	ds_read_b64 v[42:43], v180 offset:0x1000
	ds_read_b64 v[36:37], v129 offset:0x1800
	ds_read_b64 v[38:39], v180 offset:0x1800
	ds_read_b64 v[32:33], v181 offset:0
	ds_read_b64 v[34:35], v182 offset:0
	s_nop 0
	v_max_f32_e32 v78, v78, v79
	v_max3_f32 v0, v0, v2, v78
	v_pk_mul_f32 v[78:79], v[68:69], s[92:93] op_sel_hi:[1,0]
	ds_read_b64 v[28:29], v181 offset:0x800
	ds_read_b64 v[30:31], v182 offset:0x800
	ds_read_b64 v[24:25], v181 offset:0x1000
	ds_read_b64 v[26:27], v182 offset:0x1000
	ds_read_b64 v[20:21], v181 offset:0x1800
	s_nop 0
	v_max_f32_e32 v2, v78, v79
	v_pk_mul_f32 v[78:79], v[70:71], s[92:93] op_sel_hi:[1,0]
	ds_read_b64 v[22:23], v182 offset:0x1800
	s_nop 0
	v_max_f32_e32 v78, v78, v79
	v_max3_f32 v0, v0, v2, v78
	v_pk_mul_f32 v[78:79], v[72:73], s[92:93] op_sel_hi:[1,0]
	s_waitcnt lgkmcnt(0)
; template <int DK, int QB, bool NA>
; DEVI void attn_item(const AttnArgs& a, unsigned char* smem) {
;     ...
;           float mx = fmaxf(t[0][0].x, t[0][0].y);
; #pragma unroll
;           for (int kb = 0; kb < 4; ++kb)
; #pragma unroll
;             for (int h = 0; h < 2; ++h) mx = fmaxf(mx, fmaxf(t[kb][h].x, t[kb][h].y));
;           if (j == 0 || __any(mx > 6.f)) {
;             mx = xmax32(xmax16(mx));
;             const float d = (j == 0) ? mx : fmaxf(mx, 0.f);
;             const float alpha = __builtin_amdgcn_exp2f(-d);
;             const f32x2 dv = {d, d};
; #pragma unroll
;             for (int kb = 0; kb < 4; ++kb)
; #pragma unroll
;               for (int h = 0; h < 2; ++h) t[kb][h] -= dv;
;             m[qb] += d;
;             l[qb] *= alpha;
; #pragma unroll
;             for (int db = 0; db < 4; ++db) o[db][qb] *= alpha;
;           }
;           f32x2 ls2 = {0.f, 0.f};
;           unsigned pw[2][4];
; #pragma unroll
;           for (int kb = 0; kb < 4; ++kb)
; #pragma unroll
;             for (int h = 0; h < 2; ++h) {
;               const f32x2 pe = {__builtin_amdgcn_exp2f(t[kb][h].x), __builtin_amdgcn_exp2f(t[kb][h].y)};
;               ls2 += pe;
;               pw[kb >> 1][(kb & 1) * 2 + h] = pk2(pe.x, pe.y);
;             }
;           l[qb] += ls2.x + ls2.y;
; #pragma unroll
;           for (int c = 0; c < 2; ++c) {
;             const u32x4 pv = (u32x4){pw[c][0], pw[c][1], pw[c][2], pw[c][3]};
;             pf[qb][c] = __builtin_bit_cast(bf16x8, pv);
;           }
;     ...
;       asm volatile("s_waitcnt lgkmcnt(0)"
;                    : "+v"(va[0][0]), "+v"(va[0][1]), "+v"(va[0][2]), "+v"(va[0][3]), "+v"(va[1][0]), "+v"(va[1][1]), "+v"(va[1][2]), "+v"(va[1][3]),
;                      "+v"(vbq[0][0]), "+v"(vbq[0][1]), "+v"(vbq[0][2]), "+v"(vbq[0][3]), "+v"(vbq[1][0]), "+v"(vbq[1][1]), "+v"(vbq[1][2]), "+v"(vbq[1][3])
;                    :: "memory");
;       __builtin_amdgcn_sched_barrier(0);
; #pragma unroll
;       for (int c = 0; c < 2; ++c)
; #pragma unroll
;         for (int db = 0; db < 4; ++db) {
;           const u32x4 vw = (u32x4){va[c][db].x, va[c][db].y, vbq[c][db].x, vbq[c][db].y};
;           const bf16x8 vf = __builtin_bit_cast(bf16x8, vw);
; #pragma unroll
;           for (int qb = 0; qb < QB; ++qb) o[db][qb] = __builtin_amdgcn_mfma_f32_16x16x32_bf16(vf, pf[qb][c], o[db][qb], 0, 0, 0);
;         }
	s_nop 0
	v_max_f32_e32 v2, v78, v79
	v_pk_mul_f32 v[78:79], v[74:75], s[92:93] op_sel_hi:[1,0]
	s_nop 0
	v_max_f32_e32 v78, v78, v79
	v_max3_f32 v0, v0, v2, v78
	v_mov_b32_e32 v2, v0
	s_nop 1
	v_permlane16_swap_b32_e32 v0, v2
	v_max_f32_e32 v2, v2, v2
	v_max_f32_e32 v0, v0, v0
	v_max_f32_e32 v0, v0, v2
	v_mov_b32_e32 v2, v0
	s_nop 1
	v_permlane32_swap_b32_e32 v0, v2
	v_max_f32_e32 v2, v2, v2
	v_max_f32_e32 v0, v0, v0
	v_max_f32_e32 v85, v0, v2
	v_mov_b32_e32 v0, v85
	v_fma_f32 v60, v60, s92, -v0
	v_fma_f32 v61, v61, s92, -v0
	v_fma_f32 v62, v62, s92, -v0
	v_fma_f32 v63, v63, s92, -v0
	v_exp_f32_e32 v60, v60
	v_exp_f32_e32 v61, v61
	v_exp_f32_e32 v62, v62
	v_exp_f32_e32 v63, v63
	v_fma_f32 v64, v64, s92, -v0
	v_fma_f32 v65, v65, s92, -v0
	v_add_f32_e32 v78, 0, v60
	v_add_f32_e32 v79, 0, v61
	v_fma_f32 v66, v66, s92, -v0
	v_fma_f32 v67, v67, s92, -v0
	v_cvt_pk_bf16_f32 v60, v60, v61
	v_add_f32_e32 v78, v62, v78
	v_add_f32_e32 v79, v63, v79
	v_cvt_pk_bf16_f32 v61, v62, v63
	v_exp_f32_e32 v62, v64
	v_exp_f32_e32 v63, v65
	v_exp_f32_e32 v66, v66
	v_exp_f32_e32 v67, v67
	v_fma_f32 v68, v68, s92, -v0
	v_fma_f32 v69, v69, s92, -v0
	v_add_f32_e32 v64, v62, v78
	v_add_f32_e32 v65, v63, v79
	v_cvt_pk_bf16_f32 v62, v62, v63
	v_add_f32_e32 v64, v66, v64
	v_add_f32_e32 v65, v67, v65
	v_cvt_pk_bf16_f32 v63, v66, v67
	v_exp_f32_e32 v66, v68
	v_exp_f32_e32 v67, v69
	v_fma_f32 v70, v70, s92, -v0
	v_fma_f32 v71, v71, s92, -v0
	v_fma_f32 v72, v72, s92, -v0
	v_fma_f32 v73, v73, s92, -v0
	v_fma_f32 v74, v74, s92, -v0
	v_fma_f32 v75, v75, s92, -v0
	v_add_f32_e32 v68, v66, v64
	v_add_f32_e32 v69, v67, v65
	v_cvt_pk_bf16_f32 v64, v66, v67
	v_exp_f32_e32 v66, v70
	v_exp_f32_e32 v67, v71
	v_exp_f32_e32 v70, v74
	v_exp_f32_e32 v71, v75
	v_exp_f32_e64 v2, -v85
	v_add_f32_e32 v68, v66, v68
	v_add_f32_e32 v69, v67, v69
	v_cvt_pk_bf16_f32 v65, v66, v67
	v_exp_f32_e32 v66, v72
	v_exp_f32_e32 v67, v73
	v_add_f32_e32 v102, 0, v84
	v_add_f32_e32 v103, 0, v85
	v_add_f32_e32 v68, v66, v68
	v_add_f32_e32 v69, v67, v69
	s_nop 0
	v_add_f32_e32 v78, v70, v68
	v_add_f32_e32 v79, v71, v69
	v_cvt_pk_bf16_f32 v66, v66, v67
	v_cvt_pk_bf16_f32 v67, v70, v71
	v_mov_b32_e32 v70, v78
	v_mov_b32_e32 v71, v76
	v_mov_b32_e32 v76, v79
	v_add_f32_e32 v76, v70, v76
	v_add_f32_e32 v77, v71, v77
	v_pk_mul_f32 v[68:69], v[2:3], 0 op_sel_hi:[1,0]
	v_pk_fma_f32 v[100:101], v[2:3], 0, v[76:77] op_sel_hi:[1,0,1]
	v_mov_b32_e32 v72, v69
	v_mov_b32_e32 v73, v69
	v_mov_b32_e32 v74, v69
	v_mov_b32_e32 v75, v69
	v_mov_b32_e32 v69, v68
	v_mov_b32_e32 v70, v68
	v_mov_b32_e32 v71, v68
	s_setprio 1
	v_mfma_f32_16x16x32_bf16 v[76:79], v[48:51], v[52:55], v[72:75]
	s_nop 0
	v_mfma_f32_16x16x32_bf16 v[80:83], v[48:51], v[60:63], v[68:71]
	v_mfma_f32_16x16x32_bf16 v[84:87], v[44:47], v[52:55], v[72:75]
	v_mfma_f32_16x16x32_bf16 v[88:91], v[44:47], v[60:63], v[68:71]
	v_mfma_f32_16x16x32_bf16 v[92:95], v[40:43], v[52:55], v[72:75]
	v_mfma_f32_16x16x32_bf16 v[96:99], v[40:43], v[60:63], v[68:71]
	v_mfma_f32_16x16x32_bf16 v[52:55], v[36:39], v[52:55], v[72:75]
	v_mfma_f32_16x16x32_bf16 v[60:63], v[36:39], v[60:63], v[68:71]
	v_mfma_f32_16x16x32_bf16 v[48:51], v[32:35], v[56:59], v[76:79]
	v_mfma_f32_16x16x32_bf16 v[44:47], v[32:35], v[64:67], v[80:83]
	v_mfma_f32_16x16x32_bf16 v[40:43], v[28:31], v[56:59], v[84:87]
	v_mfma_f32_16x16x32_bf16 v[36:39], v[28:31], v[64:67], v[88:91]
	v_mfma_f32_16x16x32_bf16 v[32:35], v[24:27], v[56:59], v[92:95]
	v_mfma_f32_16x16x32_bf16 v[28:31], v[24:27], v[64:67], v[96:99]
	v_mfma_f32_16x16x32_bf16 v[24:27], v[20:23], v[56:59], v[52:55]
	v_mfma_f32_16x16x32_bf16 v[20:23], v[20:23], v[64:67], v[60:63]
	s_setprio 0

; DEVI unsigned pk2(float lo, float hi) { const f32x2_t v = {lo, hi}; const bf16x2_t b = __builtin_convertvector(v, bf16x2_t); return __builtin_bit_cast(unsigned, b); }
; template <int DK, int QB, bool NA>
; DEVI void attn_item(const AttnArgs& a, unsigned char* smem) {
;     ...
;           f32x2 ls2 = {0.f, 0.f};
;           unsigned pw[2][4];
; #pragma unroll
;           for (int kb = 0; kb < 4; ++kb)
; #pragma unroll
;             for (int h = 0; h < 2; ++h) {
;               const f32x2 pe = {__builtin_amdgcn_exp2f(t[kb][h].x), __builtin_amdgcn_exp2f(t[kb][h].y)};
;               ls2 += pe;
;               pw[kb >> 1][(kb & 1) * 2 + h] = pk2(pe.x, pe.y);
;             }
;           l[qb] += ls2.x + ls2.y;
; #pragma unroll
;           for (int c = 0; c < 2; ++c) {
;             const u32x4 pv = (u32x4){pw[c][0], pw[c][1], pw[c][2], pw[c][3]};
;             pf[qb][c] = __builtin_bit_cast(bf16x8, pv);
;           }
;     ...
; #pragma unroll
;       for (int c = 0; c < 2; ++c)
; #pragma unroll
;         for (int db = 0; db < 4; ++db) {
;           const u32x4 vw = (u32x4){va[c][db].x, va[c][db].y, vbq[c][db].x, vbq[c][db].y};
;           const bf16x8 vf = __builtin_bit_cast(bf16x8, vw);
; #pragma unroll
;           for (int qb = 0; qb < QB; ++qb) o[db][qb] = __builtin_amdgcn_mfma_f32_16x16x32_bf16(vf, pf[qb][c], o[db][qb], 0, 0, 0);
;         }
.LBB0_2267:
	v_exp_f32_e32 v86, v122
	v_exp_f32_e32 v87, v123
	v_exp_f32_e32 v122, v120
	v_exp_f32_e32 v123, v121
	v_exp_f32_e32 v116, v116
	v_exp_f32_e32 v117, v117
	v_add_f32_e32 v186, 0, v86
	v_add_f32_e32 v187, 0, v87
	v_exp_f32_e32 v118, v118
	v_exp_f32_e32 v119, v119
	v_cvt_pk_bf16_f32 v120, v86, v87
	v_add_f32_e32 v86, v122, v186
	v_add_f32_e32 v87, v123, v187
	v_exp_f32_e32 v114, v114
	v_exp_f32_e32 v115, v115
	v_cvt_pk_bf16_f32 v121, v122, v123
	v_add_f32_e32 v86, v116, v86
	v_add_f32_e32 v87, v117, v87
	v_cvt_pk_bf16_f32 v122, v116, v117
	v_exp_f32_e32 v116, v112
	v_exp_f32_e32 v117, v113
	v_exp_f32_e32 v110, v110
	v_exp_f32_e32 v111, v111
	v_add_f32_e32 v86, v118, v86
	v_add_f32_e32 v87, v119, v87
	v_exp_f32_e32 v2, v2
	v_exp_f32_e32 v3, v3
	v_add_f32_e32 v86, v114, v86
	v_add_f32_e32 v87, v115, v87
	v_cvt_pk_bf16_f32 v112, v114, v115
	v_add_f32_e32 v86, v116, v86
	v_add_f32_e32 v87, v117, v87
	v_cvt_pk_bf16_f32 v115, v2, v3
	v_add_f32_e32 v86, v110, v86
	v_add_f32_e32 v87, v111, v87
	v_exp_f32_e32 v96, v96
	v_add_f32_e32 v86, v2, v86
	v_add_f32_e32 v87, v3, v87
	v_exp_f32_e32 v2, v124
	v_exp_f32_e32 v3, v125
	v_add_f32_e32 v0, v86, v87
	v_exp_f32_e32 v86, v98
	v_exp_f32_e32 v87, v99
	v_exp_f32_e32 v97, v97
	v_add_f32_e32 v98, 0, v2
	v_add_f32_e32 v99, 0, v3
	v_exp_f32_e32 v94, v94
	v_exp_f32_e32 v95, v95
	v_cvt_pk_bf16_f32 v113, v116, v117
	v_cvt_pk_bf16_f32 v116, v2, v3
	v_add_f32_e32 v2, v86, v98
	v_add_f32_e32 v3, v87, v99
	v_cvt_pk_bf16_f32 v117, v86, v87
	v_exp_f32_e32 v86, v92
	v_exp_f32_e32 v87, v93
	v_exp_f32_e32 v90, v90
	v_exp_f32_e32 v91, v91
	v_add_f32_e32 v2, v96, v2
	v_add_f32_e32 v3, v97, v3
	v_exp_f32_e32 v88, v88
	v_exp_f32_e32 v89, v89
	v_add_f32_e32 v2, v94, v2
	v_add_f32_e32 v3, v95, v3
	v_exp_f32_e32 v84, v84
	v_exp_f32_e32 v85, v85
	v_add_f32_e32 v2, v86, v2
	v_add_f32_e32 v3, v87, v3
	s_waitcnt lgkmcnt(0)
	v_add_f32_e32 v101, v101, v0
	v_add_f32_e32 v2, v90, v2
	v_add_f32_e32 v3, v91, v3
	v_cvt_pk_bf16_f32 v123, v118, v119
	v_add_f32_e32 v2, v88, v2
	v_add_f32_e32 v3, v89, v3
	v_cvt_pk_bf16_f32 v114, v110, v111
	v_add_f32_e32 v2, v84, v2
	v_add_f32_e32 v3, v85, v3
	v_cvt_pk_bf16_f32 v118, v96, v97
	v_add_f32_e32 v0, v2, v3
	v_add_f32_e32 v100, v100, v0
	v_cvt_pk_bf16_f32 v119, v94, v95
	v_cvt_pk_bf16_f32 v86, v86, v87
	v_cvt_pk_bf16_f32 v87, v90, v91
	v_cvt_pk_bf16_f32 v88, v88, v89
	v_cvt_pk_bf16_f32 v89, v84, v85
	s_setprio 1
	v_mfma_f32_16x16x32_bf16 v[48:51], v[80:83], v[120:123], v[48:51]
	v_mfma_f32_16x16x32_bf16 v[44:47], v[80:83], v[116:119], v[44:47]
	v_mfma_f32_16x16x32_bf16 v[40:43], v[76:79], v[120:123], v[40:43]
	v_mfma_f32_16x16x32_bf16 v[36:39], v[76:79], v[116:119], v[36:39]
	v_mfma_f32_16x16x32_bf16 v[32:35], v[72:75], v[120:123], v[32:35]
	v_mfma_f32_16x16x32_bf16 v[28:31], v[72:75], v[116:119], v[28:31]
	v_mfma_f32_16x16x32_bf16 v[24:27], v[68:71], v[120:123], v[24:27]
	v_mfma_f32_16x16x32_bf16 v[20:23], v[68:71], v[116:119], v[20:23]
	v_mfma_f32_16x16x32_bf16 v[48:51], v[64:67], v[112:115], v[48:51]
	v_mfma_f32_16x16x32_bf16 v[44:47], v[64:67], v[86:89], v[44:47]
	v_mfma_f32_16x16x32_bf16 v[40:43], v[60:63], v[112:115], v[40:43]
	v_mfma_f32_16x16x32_bf16 v[36:39], v[60:63], v[86:89], v[36:39]
	v_mfma_f32_16x16x32_bf16 v[32:35], v[56:59], v[112:115], v[32:35]
	v_mfma_f32_16x16x32_bf16 v[28:31], v[56:59], v[86:89], v[28:31]
	v_mfma_f32_16x16x32_bf16 v[24:27], v[52:55], v[112:115], v[24:27]
	v_mfma_f32_16x16x32_bf16 v[20:23], v[52:55], v[86:89], v[20:23]
	s_setprio 0

; DEVI unsigned pk2(float lo, float hi) { const f32x2_t v = {lo, hi}; const bf16x2_t b = __builtin_convertvector(v, bf16x2_t); return __builtin_bit_cast(unsigned, b); }
; template <int DK, int QB, bool NA>
; DEVI void attn_item(const AttnArgs& a, unsigned char* smem) {
;     ...
;           f32x2 ls2 = {0.f, 0.f};
;           unsigned pw[2][4];
; #pragma unroll
;           for (int kb = 0; kb < 4; ++kb)
; #pragma unroll
;             for (int h = 0; h < 2; ++h) {
;               const f32x2 pe = {__builtin_amdgcn_exp2f(t[kb][h].x), __builtin_amdgcn_exp2f(t[kb][h].y)};
;               ls2 += pe;
;               pw[kb >> 1][(kb & 1) * 2 + h] = pk2(pe.x, pe.y);
;             }
;           l[qb] += ls2.x + ls2.y;
; #pragma unroll
;           for (int c = 0; c < 2; ++c) {
;             const u32x4 pv = (u32x4){pw[c][0], pw[c][1], pw[c][2], pw[c][3]};
;             pf[qb][c] = __builtin_bit_cast(bf16x8, pv);
;           }
;     ...
; #pragma unroll
;       for (int c = 0; c < 2; ++c)
; #pragma unroll
;         for (int db = 0; db < 4; ++db) {
;           const u32x4 vw = (u32x4){va[c][db].x, va[c][db].y, vbq[c][db].x, vbq[c][db].y};
;           const bf16x8 vf = __builtin_bit_cast(bf16x8, vw);
; #pragma unroll
;           for (int qb = 0; qb < QB; ++qb) o[db][qb] = __builtin_amdgcn_mfma_f32_16x16x32_bf16(vf, pf[qb][c], o[db][qb], 0, 0, 0);
;         }
.LBB0_2297:
	v_exp_f32_e32 v86, v116
	v_exp_f32_e32 v87, v117
	v_exp_f32_e32 v116, v114
	v_exp_f32_e32 v117, v115
	v_exp_f32_e32 v110, v110
	v_exp_f32_e32 v111, v111
	v_add_f32_e32 v120, 0, v86
	v_add_f32_e32 v121, 0, v87
	v_exp_f32_e32 v112, v112
	v_exp_f32_e32 v113, v113
	v_cvt_pk_bf16_f32 v114, v86, v87
	v_add_f32_e32 v86, v116, v120
	v_add_f32_e32 v87, v117, v121
	v_exp_f32_e32 v108, v108
	v_exp_f32_e32 v109, v109
	v_cvt_pk_bf16_f32 v115, v116, v117
	v_add_f32_e32 v86, v110, v86
	v_add_f32_e32 v87, v111, v87
	v_cvt_pk_bf16_f32 v116, v110, v111
	v_exp_f32_e32 v110, v106
	v_exp_f32_e32 v111, v107
	v_exp_f32_e32 v104, v104
	v_exp_f32_e32 v105, v105
	v_add_f32_e32 v86, v112, v86
	v_add_f32_e32 v87, v113, v87
	v_exp_f32_e32 v2, v2
	v_exp_f32_e32 v3, v3
	v_add_f32_e32 v86, v108, v86
	v_add_f32_e32 v87, v109, v87
	v_cvt_pk_bf16_f32 v106, v108, v109
	v_add_f32_e32 v86, v110, v86
	v_add_f32_e32 v87, v111, v87
	v_cvt_pk_bf16_f32 v109, v2, v3
	v_add_f32_e32 v86, v104, v86
	v_add_f32_e32 v87, v105, v87
	v_exp_f32_e32 v96, v96
	v_add_f32_e32 v86, v2, v86
	v_add_f32_e32 v87, v3, v87
	v_exp_f32_e32 v2, v118
	v_exp_f32_e32 v3, v119
	v_add_f32_e32 v0, v86, v87
	v_exp_f32_e32 v86, v98
	v_exp_f32_e32 v87, v99
	v_exp_f32_e32 v97, v97
	v_add_f32_e32 v98, 0, v2
	v_add_f32_e32 v99, 0, v3
	v_exp_f32_e32 v94, v94
	v_exp_f32_e32 v95, v95
	v_cvt_pk_bf16_f32 v107, v110, v111
	v_cvt_pk_bf16_f32 v110, v2, v3
	v_add_f32_e32 v2, v86, v98
	v_add_f32_e32 v3, v87, v99
	v_cvt_pk_bf16_f32 v111, v86, v87
	v_exp_f32_e32 v86, v92
	v_exp_f32_e32 v87, v93
	v_exp_f32_e32 v90, v90
	v_exp_f32_e32 v91, v91
	v_add_f32_e32 v2, v96, v2
	v_add_f32_e32 v3, v97, v3
	v_exp_f32_e32 v88, v88
	v_exp_f32_e32 v89, v89
	v_add_f32_e32 v2, v94, v2
	v_add_f32_e32 v3, v95, v3
	v_exp_f32_e32 v84, v84
	v_exp_f32_e32 v85, v85
	v_add_f32_e32 v2, v86, v2
	v_add_f32_e32 v3, v87, v3
	s_waitcnt lgkmcnt(0)
	v_add_f32_e32 v101, v101, v0
	v_add_f32_e32 v2, v90, v2
	v_add_f32_e32 v3, v91, v3
	v_cvt_pk_bf16_f32 v117, v112, v113
	v_add_f32_e32 v2, v88, v2
	v_add_f32_e32 v3, v89, v3
	v_cvt_pk_bf16_f32 v108, v104, v105
	v_add_f32_e32 v2, v84, v2
	v_add_f32_e32 v3, v85, v3
	v_cvt_pk_bf16_f32 v112, v96, v97
	v_add_f32_e32 v0, v2, v3
	v_add_f32_e32 v100, v100, v0
	v_cvt_pk_bf16_f32 v113, v94, v95
	v_cvt_pk_bf16_f32 v86, v86, v87
	v_cvt_pk_bf16_f32 v87, v90, v91
	v_cvt_pk_bf16_f32 v88, v88, v89
	v_cvt_pk_bf16_f32 v89, v84, v85
	s_setprio 1
	v_mfma_f32_16x16x32_bf16 v[48:51], v[80:83], v[114:117], v[48:51]
	v_mfma_f32_16x16x32_bf16 v[44:47], v[80:83], v[110:113], v[44:47]
	v_mfma_f32_16x16x32_bf16 v[40:43], v[76:79], v[114:117], v[40:43]
	v_mfma_f32_16x16x32_bf16 v[36:39], v[76:79], v[110:113], v[36:39]
	v_mfma_f32_16x16x32_bf16 v[32:35], v[72:75], v[114:117], v[32:35]
	v_mfma_f32_16x16x32_bf16 v[28:31], v[72:75], v[110:113], v[28:31]
	v_mfma_f32_16x16x32_bf16 v[24:27], v[68:71], v[114:117], v[24:27]
	v_mfma_f32_16x16x32_bf16 v[20:23], v[68:71], v[110:113], v[20:23]
	v_mfma_f32_16x16x32_bf16 v[48:51], v[64:67], v[106:109], v[48:51]
	v_mfma_f32_16x16x32_bf16 v[44:47], v[64:67], v[86:89], v[44:47]
	v_mfma_f32_16x16x32_bf16 v[40:43], v[60:63], v[106:109], v[40:43]
	v_mfma_f32_16x16x32_bf16 v[36:39], v[60:63], v[86:89], v[36:39]
	v_mfma_f32_16x16x32_bf16 v[32:35], v[56:59], v[106:109], v[32:35]
	v_mfma_f32_16x16x32_bf16 v[28:31], v[56:59], v[86:89], v[28:31]
	v_mfma_f32_16x16x32_bf16 v[24:27], v[52:55], v[106:109], v[24:27]
	v_mfma_f32_16x16x32_bf16 v[20:23], v[52:55], v[86:89], v[20:23]
	s_setprio 0

; DEVI unsigned pk2(float lo, float hi) { const f32x2_t v = {lo, hi}; const bf16x2_t b = __builtin_convertvector(v, bf16x2_t); return __builtin_bit_cast(unsigned, b); }
; DEVI size_t blk_off(int row, int col) { return ((size_t)(col >> 5) * MROWS + row) * 32 + (col & 31); }
; DEVI float xsum16(float x) { auto r = __builtin_amdgcn_permlane16_swap(__float_as_uint(x), __float_as_uint(x), false, false); return __uint_as_float(r[0]) + __uint_as_float(r[1]); }
; DEVI float xsum32(float x) { auto r = __builtin_amdgcn_permlane32_swap(__float_as_uint(x), __float_as_uint(x), false, false); return __uint_as_float(r[0]) + __uint_as_float(r[1]); }
; template <int DK, int QB, bool NA>
; DEVI void attn_item(const AttnArgs& a, unsigned char* smem) {
;     ...
;           f32x2 ls2 = {0.f, 0.f};
;           unsigned pw[2][4];
; #pragma unroll
;           for (int kb = 0; kb < 4; ++kb)
; #pragma unroll
;             for (int h = 0; h < 2; ++h) {
;               const f32x2 pe = {__builtin_amdgcn_exp2f(t[kb][h].x), __builtin_amdgcn_exp2f(t[kb][h].y)};
;               ls2 += pe;
;               pw[kb >> 1][(kb & 1) * 2 + h] = pk2(pe.x, pe.y);
;             }
;           l[qb] += ls2.x + ls2.y;
; #pragma unroll
;           for (int c = 0; c < 2; ++c) {
;             const u32x4 pv = (u32x4){pw[c][0], pw[c][1], pw[c][2], pw[c][3]};
;             pf[qb][c] = __builtin_bit_cast(bf16x8, pv);
;           }
;     ...
;   if (wact) {
; #pragma unroll
;     for (int qb = 0; qb < QB; ++qb) {
;       const float lt = xsum32(xsum16(l[qb]));
;       const float inv = 1.0f / lt;
;       const int qi = w * QB * 16 + qb * 16 + l16;
;       if (qi < a.nq) {
; #pragma unroll
;         for (int db = 0; db < 4; ++db) {
;           const f32x4 v = o[db][qb] * inv;
;           *(u32x2*)(a.O + blk_off(a.orow0 + qi, a.ocol0 + db * 16 + g * 4)) = (u32x2){pk2(v[0], v[1]), pk2(v[2], v[3])};
;         }
;       }
.LBB0_2303:
	v_exp_f32_e32 v74, v74
	v_exp_f32_e32 v75, v75
	v_exp_f32_e32 v72, v72
	v_exp_f32_e32 v73, v73
	v_exp_f32_e32 v18, v18
	v_exp_f32_e32 v19, v19
	v_add_f32_e32 v80, 0, v74
	v_add_f32_e32 v81, 0, v75
	v_cvt_pk_bf16_f32 v78, v74, v75
	v_add_f32_e32 v74, v72, v80
	v_add_f32_e32 v75, v73, v81
	v_cvt_pk_bf16_f32 v79, v72, v73
	v_add_f32_e32 v72, v18, v74
	v_add_f32_e32 v73, v19, v75
	v_exp_f32_e32 v70, v70
	v_add_f32_e32 v72, v18, v72
	v_add_f32_e32 v73, v19, v73
	v_exp_f32_e32 v71, v71
	v_add_f32_e32 v72, v18, v72
	v_add_f32_e32 v73, v19, v73
	v_cvt_pk_bf16_f32 v80, v18, v19
	v_add_f32_e32 v72, v18, v72
	v_add_f32_e32 v73, v19, v73
	v_exp_f32_e32 v68, v68
	v_add_f32_e32 v72, v18, v72
	v_add_f32_e32 v73, v19, v73
	v_exp_f32_e32 v69, v69
	v_add_f32_e32 v18, v18, v72
	v_add_f32_e32 v19, v19, v73
	v_exp_f32_e32 v72, v76
	v_exp_f32_e32 v73, v77
	s_waitcnt lgkmcnt(0)
	v_add_f32_e32 v0, v18, v19
	v_add_f32_e32 v0, v101, v0
	v_cvt_pk_bf16_f32 v76, v70, v71
	v_mov_b32_e32 v81, v80
	v_mov_b32_e32 v82, v80
	v_mov_b32_e32 v83, v80
	v_mov_b32_e32 v84, v80
	v_mov_b32_e32 v85, v80
	v_cvt_pk_bf16_f32 v74, v68, v69
	v_cvt_pk_bf16_f32 v75, v72, v73
	v_mov_b32_e32 v77, v76
	v_mov_b32_e32 v86, v76
	v_mov_b32_e32 v87, v76
	v_mov_b32_e32 v88, v76
	v_mov_b32_e32 v89, v76
	s_setprio 1
	v_mfma_f32_16x16x32_bf16 v[40:43], v[60:63], v[78:81], v[40:43]
	v_mfma_f32_16x16x32_bf16 v[36:39], v[60:63], v[74:77], v[36:39]
	v_mfma_f32_16x16x32_bf16 v[48:51], v[64:67], v[78:81], v[48:51]
	v_mfma_f32_16x16x32_bf16 v[44:47], v[64:67], v[74:77], v[44:47]
	v_mfma_f32_16x16x32_bf16 v[60:63], v[56:59], v[78:81], v[32:35]
	v_mfma_f32_16x16x32_bf16 v[56:59], v[56:59], v[74:77], v[28:31]
	s_nop 1
	v_or_b32_e32 v35, v128, v126
	v_lshlrev_b32_e32 v34, 2, v127
	v_cmp_gt_i32_e32 vcc, s57, v35
	v_mfma_f32_16x16x32_bf16 v[26:29], v[52:55], v[78:81], v[24:27]
	v_mfma_f32_16x16x32_bf16 v[52:55], v[52:55], v[74:77], v[20:23]
	v_mfma_f32_16x16x32_bf16 v[22:25], v[10:13], v[82:85], v[40:43]
	v_mfma_f32_16x16x32_bf16 v[10:13], v[10:13], v[86:89], v[36:39]
	s_nop 2
	v_mov_b32_e32 v36, v0
	v_mfma_f32_16x16x32_bf16 v[30:33], v[14:17], v[82:85], v[48:51]
	s_nop 0
	v_permlane16_swap_b32_e32 v0, v36
	v_add_f32_e32 v36, v0, v36
	v_mfma_f32_16x16x32_bf16 v[14:17], v[14:17], v[86:89], v[44:47]
	v_mov_b32_e32 v37, v36
	s_nop 1
	v_permlane32_swap_b32_e32 v36, v37
	v_mfma_f32_16x16x32_bf16 v[18:21], v[6:9], v[82:85], v[60:63]
	v_lshlrev_b32_e32 v0, 1, v34
	v_mfma_f32_16x16x32_bf16 v[6:9], v[6:9], v[86:89], v[56:59]
	v_mfma_f32_16x16x32_bf16 v[26:29], v[2:5], v[82:85], v[26:29]
	v_mfma_f32_16x16x32_bf16 v[2:5], v[2:5], v[86:89], v[52:55]
	s_setprio 0
	s_and_saveexec_b64 s[0:1], vcc
	s_cbranch_execz .LBB0_2305
	v_add_f32_e32 v36, v36, v37
	v_div_scale_f32 v37, s[8:9], v36, v36, 1.0
	v_rcp_f32_e32 v38, v37
	v_div_scale_f32 v39, vcc, 1.0, v36, 1.0
	s_lshl_b32 s3, s58, 1
	v_fma_f32 v40, -v37, v38, 1.0
	v_fmac_f32_e32 v38, v40, v38
	v_mul_f32_e32 v40, v39, v38
	v_fma_f32 v41, -v37, v40, v39
	v_fmac_f32_e32 v40, v41, v38
	v_fma_f32 v37, -v37, v40, v39
	v_div_fmas_f32 v37, v37, v38, v40
	v_div_fixup_f32 v36, v37, v36, 1.0
	v_pk_mul_f32 v[32:33], v[32:33], v[36:37] op_sel_hi:[1,0]
	v_pk_mul_f32 v[30:31], v[30:31], v[36:37] op_sel_hi:[1,0]
	v_pk_mul_f32 v[20:21], v[20:21], v[36:37] op_sel_hi:[1,0]
	v_cvt_pk_bf16_f32 v30, v30, v31
	v_cvt_pk_bf16_f32 v31, v32, v33
	v_add_u32_e32 v32, s59, v35
	v_ashrrev_i32_e32 v33, 31, v32
	v_mad_u64_u32 v[38:39], s[8:9], s3, v206, v[32:33]
	v_pk_mul_f32 v[18:19], v[18:19], v[36:37] op_sel_hi:[1,0]
	s_or_b32 s3, s3, 1
	v_readlane_b32 s28, v251, 54
	v_cvt_pk_bf16_f32 v18, v18, v19
	v_cvt_pk_bf16_f32 v19, v20, v21
	v_mad_u64_u32 v[20:21], s[8:9], s3, v206, v[32:33]
	v_lshlrev_b64 v[38:39], 6, v[38:39]
	v_readlane_b32 s29, v251, 55
	v_lshlrev_b64 v[20:21], 6, v[20:21]
	v_pk_mul_f32 v[24:25], v[24:25], v[36:37] op_sel_hi:[1,0]
	v_lshl_add_u64 v[38:39], s[28:29], 0, v[38:39]
	v_pk_mul_f32 v[22:23], v[22:23], v[36:37] op_sel_hi:[1,0]
	v_lshl_add_u64 v[20:21], s[28:29], 0, v[20:21]
	v_lshl_add_u64 v[38:39], v[38:39], 0, v[0:1]
	v_cvt_pk_bf16_f32 v22, v22, v23
	v_cvt_pk_bf16_f32 v23, v24, v25
	v_lshl_add_u64 v[20:21], v[20:21], 0, v[0:1]
	global_store_dwordx2 v[38:39], v[22:23], off offset:32
	global_store_dwordx2 v[20:21], v[18:19], off
	v_pk_mul_f32 v[18:19], v[28:29], v[36:37] op_sel_hi:[1,0]
	v_pk_mul_f32 v[20:21], v[26:27], v[36:37] op_sel_hi:[1,0]
	v_or_b32_e32 v22, s56, v34
	v_cvt_pk_bf16_f32 v20, v20, v21
	v_cvt_pk_bf16_f32 v21, v18, v19
	v_or_b32_e32 v18, 48, v22
	v_lshrrev_b32_e32 v18, 5, v18
	v_mad_u64_u32 v[18:19], s[8:9], v18, s93, v[32:33]
	v_bitop3_b32 v22, v22, 28, 48 bitop3:0xc8
	v_lshlrev_b64 v[18:19], 6, v[18:19]
	v_lshl_add_u64 v[18:19], s[28:29], 0, v[18:19]
	v_lshlrev_b32_e32 v22, 1, v22
	v_mov_b32_e32 v23, v1
	v_lshl_add_u64 v[18:19], v[18:19], 0, v[22:23]
	global_store_dwordx2 v[38:39], v[30:31], off
	global_store_dwordx2 v[18:19], v[20:21], off
; DEVI unsigned pk2(float lo, float hi) { const f32x2_t v = {lo, hi}; const bf16x2_t b = __builtin_convertvector(v, bf16x2_t); return __builtin_bit_cast(unsigned, b); }
; DEVI size_t blk_off(int row, int col) { return ((size_t)(col >> 5) * MROWS + row) * 32 + (col & 31); }
; DEVI float xsum16(float x) { auto r = __builtin_amdgcn_permlane16_swap(__float_as_uint(x), __float_as_uint(x), false, false); return __uint_as_float(r[0]) + __uint_as_float(r[1]); }
; DEVI float xsum32(float x) { auto r = __builtin_amdgcn_permlane32_swap(__float_as_uint(x), __float_as_uint(x), false, false); return __uint_as_float(r[0]) + __uint_as_float(r[1]); }
; template <int DK, int QB, bool NA>
; DEVI void attn_item(const AttnArgs& a, unsigned char* smem) {
;     ...
;           f32x2 ls2 = {0.f, 0.f};
;           unsigned pw[2][4];
; #pragma unroll
;           for (int kb = 0; kb < 4; ++kb)
; #pragma unroll
;             for (int h = 0; h < 2; ++h) {
;               const f32x2 pe = {__builtin_amdgcn_exp2f(t[kb][h].x), __builtin_amdgcn_exp2f(t[kb][h].y)};
;               ls2 += pe;
;               pw[kb >> 1][(kb & 1) * 2 + h] = pk2(pe.x, pe.y);
;             }
;           l[qb] += ls2.x + ls2.y;
;     ...
;   if (wact) {
; #pragma unroll
;     for (int qb = 0; qb < QB; ++qb) {
;       const float lt = xsum32(xsum16(l[qb]));
;       const float inv = 1.0f / lt;
;       const int qi = w * QB * 16 + qb * 16 + l16;
;       if (qi < a.nq) {
; #pragma unroll
;         for (int db = 0; db < 4; ++db) {
;           const f32x4 v = o[db][qb] * inv;
;           *(u32x2*)(a.O + blk_off(a.orow0 + qi, a.ocol0 + db * 16 + g * 4)) = (u32x2){pk2(v[0], v[1]), pk2(v[2], v[3])};
;         }
;       }
.LBB0_2305:
	s_or_b64 exec, exec, s[0:1]
	s_nop 0
	v_add_f32_e32 v18, 0, v68
	v_add_f32_e32 v19, 0, v69
	s_mov_b64 s[8:9], 0
	v_add_f32_e32 v18, v72, v18
	v_add_f32_e32 v19, v73, v19
	s_nop 0
	v_add_f32_e32 v18, v70, v18
	v_add_f32_e32 v19, v71, v19
	s_nop 0
	v_add_f32_e32 v18, v70, v18
	v_add_f32_e32 v19, v71, v19
	s_nop 0
	v_add_f32_e32 v18, v70, v18
	v_add_f32_e32 v19, v71, v19
	s_nop 0
	v_add_f32_e32 v18, v70, v18
	v_add_f32_e32 v19, v71, v19
	s_nop 0
	v_add_f32_e32 v18, v70, v18
	v_add_f32_e32 v19, v71, v19
	s_nop 0
	v_add_f32_e32 v18, v70, v18
	v_add_f32_e32 v19, v71, v19
	s_nop 0
	v_add_f32_e32 v18, v18, v19
	v_add_f32_e32 v18, v100, v18
	v_mov_b32_e32 v19, v18
	s_nop 1
	v_permlane16_swap_b32_e32 v18, v19
	v_add_f32_e32 v19, v18, v19
	v_mov_b32_e32 v20, v19
	v_or_b32_e32 v18, 16, v35
	s_nop 0
	v_permlane32_swap_b32_e32 v19, v20
	v_cmp_gt_i32_e32 vcc, s57, v18
	s_and_saveexec_b64 s[0:1], vcc
	s_xor_b64 s[0:1], exec, s[0:1]
	s_cbranch_execz .LBB0_2307
	v_add_f32_e32 v19, v19, v20
	v_div_scale_f32 v20, s[8:9], v19, v19, 1.0
	v_rcp_f32_e32 v21, v20
	s_lshl_b32 s3, s58, 1
	v_readlane_b32 s28, v251, 54
	v_readlane_b32 s29, v251, 55
	v_fma_f32 v22, -v20, v21, 1.0
	v_fmac_f32_e32 v21, v22, v21
	v_div_scale_f32 v22, vcc, 1.0, v19, 1.0
	v_mul_f32_e32 v23, v22, v21
	v_fma_f32 v24, -v20, v23, v22
	v_fmac_f32_e32 v23, v24, v21
	v_fma_f32 v20, -v20, v23, v22
	v_div_fmas_f32 v20, v20, v21, v23
	v_div_fixup_f32 v20, v20, v19, 1.0
	v_pk_mul_f32 v[16:17], v[16:17], v[20:21] op_sel_hi:[1,0]
	v_pk_mul_f32 v[14:15], v[14:15], v[20:21] op_sel_hi:[1,0]
	v_pk_mul_f32 v[8:9], v[8:9], v[20:21] op_sel_hi:[1,0]
	v_cvt_pk_bf16_f32 v14, v14, v15
	v_cvt_pk_bf16_f32 v15, v16, v17
	v_add_u32_e32 v16, s59, v18
	v_ashrrev_i32_e32 v17, 31, v16
	v_mad_u64_u32 v[18:19], s[8:9], s3, v206, v[16:17]
	v_pk_mul_f32 v[6:7], v[6:7], v[20:21] op_sel_hi:[1,0]
	s_or_b32 s3, s3, 1
	v_cvt_pk_bf16_f32 v6, v6, v7
	v_cvt_pk_bf16_f32 v7, v8, v9
	v_mad_u64_u32 v[8:9], s[8:9], s3, v206, v[16:17]
	v_lshlrev_b64 v[18:19], 6, v[18:19]
	v_lshlrev_b64 v[8:9], 6, v[8:9]
	v_lshl_add_u64 v[18:19], s[28:29], 0, v[18:19]
	v_lshl_add_u64 v[8:9], s[28:29], 0, v[8:9]
	v_or3_b32 v64, s56, v34, 48
	v_lshl_add_u64 v[18:19], v[18:19], 0, v[0:1]
	v_lshl_add_u64 v[8:9], v[8:9], 0, v[0:1]
	v_lshrrev_b32_e32 v0, 5, v64
	v_pk_mul_f32 v[12:13], v[12:13], v[20:21] op_sel_hi:[1,0]
	v_pk_mul_f32 v[10:11], v[10:11], v[20:21] op_sel_hi:[1,0]
	v_pk_mul_f32 v[4:5], v[4:5], v[20:21] op_sel_hi:[1,0]
	v_pk_mul_f32 v[2:3], v[2:3], v[20:21] op_sel_hi:[1,0]
	v_mad_u64_u32 v[62:63], s[8:9], v0, s93, v[16:17]
	v_cvt_pk_bf16_f32 v10, v10, v11
	v_cvt_pk_bf16_f32 v11, v12, v13
	v_cvt_pk_bf16_f32 v60, v2, v3
	v_cvt_pk_bf16_f32 v61, v4, v5
	s_mov_b64 s[8:9], exec
	global_store_dwordx2 v[18:19], v[14:15], off
	global_store_dwordx2 v[18:19], v[10:11], off offset:32
	global_store_dwordx2 v[8:9], v[6:7], off

; #define RAW_BARRIER() do { asm volatile("s_waitcnt lgkmcnt(0)" ::: "memory"); __builtin_amdgcn_s_barrier(); } while (0)
; template <int DK, int QB, bool NA>
; DEVI void attn_item(const AttnArgs& a, unsigned char* smem) {
;     ...
;   bf16x8 qf[QB][KS];
; #pragma unroll
;   for (int qb = 0; qb < QB; ++qb) {
;     const bf16_t* qp = a.Q + (size_t)((wact ? w * QB * 16 : 0) + qb * 16 + l16) * a.ldq + g * 8;
; #pragma unroll
;     for (int ks = 0; ks < KS; ++ks) qf[qb][ks] = *(const bf16x8*)(qp + ks * 32);
;   }
;   float m[QB], l[QB];
;   f32x4 o[4][QB];
; #pragma unroll
;   for (int qb = 0; qb < QB; ++qb) {
;     m[qb] = NA ? -1e30f : 0.f; l[qb] = 0.f;
; #pragma unroll
;     for (int db = 0; db < 4; ++db) o[db][qb] = (f32x4){0.f, 0.f, 0.f, 0.f};
;   }
;   const int r8 = tid >> 3, c8 = (tid & 7) ^ ((tid >> 4) & 7);
;   const bf16_t* Kn = a.K + (size_t)r8 * a.ldk + c8 * 8;
;   const bf16_t* Kr = a.K + (size_t)(tid >> 2) * a.ldk + 64 + (((tid & 3) ^ ((0 - (tid >> 4)) & 3)) * 8);
;   const bf16_t* Vg = a.Vt + (size_t)r8 * a.Lk + c8 * 8;
;   const size_t kstep = (size_t)32 * a.ldk, vstep = (size_t)32 * a.Lk;
;   unsigned char* lds_t = smem + tid * 16;
;     ...
;   asm volatile("s_waitcnt vmcnt(0)" ::: "memory");
;   RAW_BARRIER();
;   ATT_ISSUE(0, 0);
;   if (nt > 1) ATT_ISSUE(1, 1);
;   const int sw8 = (l16 >> 1) & 7, vsw = sw8 << 1;
;   const unsigned ka0 = l16 * 128 + ((g ^ sw8) << 4), ka1 = l16 * 128 + (((4 + g) ^ sw8) << 4);
;   const unsigned kr = 8192 + l16 * 64 + ((g ^ ((0 - (l16 >> 2)) & 3)) << 4);
;   const unsigned vb00 = 12288 + l16 * 128 + (((0 + g) ^ vsw) << 3), vb01 = 12288 + l16 * 128 + (((4 + g) ^ vsw) << 3);
;   const unsigned vb10 = 12288 + l16 * 128 + (((8 + g) ^ vsw) << 3), vb11 = 12288 + l16 * 128 + (((12 + g) ^ vsw) << 3);
;   const unsigned biasA = lbase + ATT_BIAS_OFF;
;   const int qc = w * 16 + l16;
;   const int cs0 = min(max(qc - 8, 0), 48);
;   int cs = 0, is = 2;
; DEVI void attn_dense_phase(const Params& p, unsigned char* smem, unsigned* ctr) {
;     ...
;     if (h16 < 8) {
;       a.Q = Hb + H_QA + (size_t)q0 * 768 + h16 * 96; a.ldq = 768;
;       a.K = Hb + H_KMLA + (size_t)kb * 768 + h16 * 96; a.ldk = 768;
;       a.Vt = Hb + H_VTM + (size_t)512 * kb + (size_t)(h16 * 64) * Lk;
;       a.sc2 = 0.10206207261596577f * LOG2E;
;       attn_item<96, 2, false>(a, smem);
.LBB0_2309:
	s_mul_i32 s1, s59, 0x600
	v_readlane_b32 s3, v251, 58
	s_mul_hi_i32 s0, s59, 0x600
	s_add_u32 s3, s3, s1
	v_readlane_b32 s1, v251, 59
	s_mul_i32 s20, s58, 0x60
	s_addc_u32 s9, s1, s0
	s_lshl_b64 s[0:1], s[20:21], 1
	s_add_u32 s8, s3, s0
	s_addc_u32 s9, s9, s1
	s_ashr_i32 s3, s2, 31
	s_mul_i32 s40, s2, 0x600
	v_readlane_b32 s28, v251, 60
	s_mul_hi_i32 s20, s2, 0x600
	s_add_u32 s40, s28, s40
	v_readlane_b32 s28, v251, 61
	s_addc_u32 s20, s28, s20
	s_add_u32 s40, s40, s0
	s_addc_u32 s41, s20, s1
	s_lshl_b64 s[0:1], s[2:3], 10
	v_readlane_b32 s2, v251, 62
	s_add_u32 s2, s2, s0
	v_readlane_b32 s0, v251, 63
	s_mul_i32 s20, s62, s56
	v_mov_b32_e32 v2, v177
	s_addc_u32 s3, s0, s1
	s_lshl_b64 s[0:1], s[20:21], 1
	s_add_u32 s2, s2, s0
	v_ashrrev_i32_e32 v0, 1, v2
	v_and_b32_e32 v208, 0xffffffe0, v0
	s_addc_u32 s3, s3, s1
	v_cmp_gt_i32_e64 s[0:1], s57, v208
	v_and_b32_e32 v186, 15, v2
	v_bfe_u32 v187, v2, 4, 2
	v_cndmask_b32_e64 v0, 0, v208, s[0:1]
	v_or_b32_e32 v3, v0, v186
	v_lshlrev_b32_e32 v0, 4, v187
	v_lshl_add_u64 v[4:5], s[8:9], 0, v[0:1]
	s_movk_i32 s20, 0x600
	v_or_b32_e32 v0, 16, v3
	v_ashrrev_i32_e32 v32, 4, v2
	v_mad_i64_i32 v[6:7], s[8:9], v3, s20, v[4:5]
	v_mad_i64_i32 v[4:5], s[8:9], v0, s20, v[4:5]
	v_xor_b32_e32 v0, v32, v2
	v_ashrrev_i32_e32 v3, 3, v2
	v_mov_b64_e32 v[28:29], s[40:41]
	v_lshlrev_b32_e32 v0, 4, v0
	v_mad_i64_i32 v[30:31], s[8:9], v3, s20, v[28:29]
	v_and_b32_e32 v0, 0x70, v0
	v_lshl_add_u64 v[114:115], v[30:31], 0, v[0:1]
	v_ashrrev_i32_e32 v30, 2, v2
	v_mad_i64_i32 v[28:29], s[8:9], v30, s20, v[28:29]
	v_sub_u32_e32 v30, 0, v32
	v_xor_b32_e32 v30, v2, v30
	v_lshlrev_b32_e32 v30, 4, v30
	v_and_b32_e32 v30, 48, v30
	v_mov_b32_e32 v31, v1
	v_lshl_add_u64 v[116:117], v[28:29], 0, v[30:31]
	v_mad_i64_i32 v[30:31], s[8:9], v3, s62, 0
	v_lshl_add_u64 v[30:31], v[30:31], 1, s[2:3]
	v_lshlrev_b32_e32 v216, 4, v2
	v_lshl_add_u64 v[112:113], v[30:31], 0, v[0:1]
	v_readfirstlane_b32 s2, v216
	v_add_u32_e32 v0, 0x1000, v216
	global_load_dwordx4 v[24:27], v[6:7], off
	global_load_dwordx4 v[16:19], v[6:7], off offset:64
	global_load_dwordx4 v[8:11], v[6:7], off offset:128
	global_load_dwordx4 v[20:23], v[4:5], off
	global_load_dwordx4 v[12:15], v[4:5], off offset:64
	s_nop 0
	global_load_dwordx4 v[4:7], v[4:5], off offset:128
	s_waitcnt vmcnt(0)
	s_mov_b32 m0, s2
	v_readfirstlane_b32 s2, v0
	v_add_u32_e32 v0, 0x2000, v216
	s_mov_b64 s[40:41], 0x80
	s_waitcnt lgkmcnt(0)
	s_barrier
	global_load_lds_dwordx4 v[114:115], off
	v_lshl_add_u64 v[30:31], v[114:115], 0, s[86:87]
	s_mov_b32 m0, s2
	v_readfirstlane_b32 s2, v0
	v_add_u32_e32 v0, 0x3000, v216
	v_lshl_add_u64 v[28:29], v[116:117], 0, s[40:41]
	global_load_lds_dwordx4 v[30:31], off
	s_mov_b32 m0, s2
	v_readfirstlane_b32 s2, v0
	v_add_u32_e32 v0, 0x4000, v216
	global_load_lds_dwordx4 v[28:29], off
	s_mov_b32 m0, s2
	s_lshl_b32 s20, s62, 6
	v_readfirstlane_b32 s2, v0
	v_add_u32_e32 v0, 0x5000, v216
	global_load_lds_dwordx4 v[112:113], off
	v_lshl_add_u64 v[118:119], v[112:113], 0, s[20:21]
	s_mov_b32 m0, s2
	v_readfirstlane_b32 s2, v0
	global_load_lds_dwordx4 v[118:119], off
	v_lshl_add_u64 v[28:29], v[114:115], 0, s[38:39]
	s_mov_b32 m0, s2
	s_mov_b64 s[2:3], 0x24000
	v_add_u32_e32 v0, 0x6000, v216
	global_load_lds_dwordx4 v[28:29], off
	v_lshl_add_u64 v[28:29], v[114:115], 0, s[2:3]
	v_readfirstlane_b32 s2, v0
	s_mov_b32 m0, s2
	s_mov_b64 s[2:3], 0x18080
	v_add_u32_e32 v0, 0x7000, v216
	global_load_lds_dwordx4 v[28:29], off
	v_lshl_add_u64 v[28:29], v[116:117], 0, s[2:3]
	v_readfirstlane_b32 s2, v0
	v_add_u32_e32 v0, 0x8000, v216
	s_mov_b32 m0, s2
	v_readfirstlane_b32 s2, v0
	v_add_u32_e32 v0, 0x9000, v216
	global_load_lds_dwordx4 v[28:29], off
	v_lshl_add_u64 v[28:29], v[112:113], 0, s[40:41]
	s_mov_b32 m0, s2
	v_readfirstlane_b32 s2, v0
	global_load_lds_dwordx4 v[28:29], off
	v_lshl_add_u64 v[28:29], v[118:119], 0, s[40:41]
	s_mov_b32 m0, s2
	v_add_u32_e32 v0, 0xa000, v216
	global_load_lds_dwordx4 v[28:29], off
	v_readfirstlane_b32 s2, v0
	s_waitcnt vmcnt(5)
	v_lshl_add_u64 v[28:29], v[114:115], 0, s[4:5]
	s_mov_b32 m0, s2
	s_mov_b64 s[2:3], 0x3c000
	v_add_u32_e32 v0, 0xb000, v216
	s_waitcnt lgkmcnt(0)
	s_barrier
	global_load_lds_dwordx4 v[28:29], off
	v_lshl_add_u64 v[28:29], v[114:115], 0, s[2:3]
	v_readfirstlane_b32 s2, v0
	s_mov_b32 m0, s2
	s_mov_b64 s[2:3], 0x30080
	v_add_u32_e32 v0, 0xc000, v216
	global_load_lds_dwordx4 v[28:29], off
	v_lshl_add_u64 v[28:29], v[116:117], 0, s[2:3]
	v_readfirstlane_b32 s2, v0
	v_add_u32_e32 v0, 0xd000, v216
	s_mov_b32 m0, s2
	s_mov_b64 s[8:9], 0x100
	v_readfirstlane_b32 s2, v0
	v_add_u32_e32 v0, 0xe000, v216
	global_load_lds_dwordx4 v[28:29], off
	v_lshl_add_u64 v[28:29], v[112:113], 0, s[8:9]
	s_mov_b32 m0, s2
	v_readfirstlane_b32 s2, v0
	global_load_lds_dwordx4 v[28:29], off
	v_lshl_add_u64 v[28:29], v[118:119], 0, s[8:9]
	s_mov_b32 m0, s2
	s_mov_b64 s[28:29], 0x80
	global_load_lds_dwordx4 v[28:29], off
	v_cmp_le_i32_e32 vcc, s57, v208
	s_and_saveexec_b64 s[2:3], vcc
	s_xor_b64 s[2:3], exec, s[2:3]
	s_or_saveexec_b64 s[2:3], s[2:3]
	v_lshrrev_b32_e32 v0, 4, v2
	v_bfe_u32 v3, v2, 1, 3
	v_lshrrev_b32_e32 v2, 2, v2
	v_lshlrev_b32_e32 v28, 1, v3
	v_lshlrev_b32_e32 v29, 7, v186
	v_bitop3_b32 v30, v0, v3, 3 bitop3:0x6c
	v_bitop3_b32 v3, v187, v3, 4 bitop3:0x36
	v_sub_u32_e32 v2, 0, v2
	v_lshl_or_b32 v213, v30, 4, v29
	v_lshl_or_b32 v214, v3, 4, v29
	v_or_b32_e32 v3, 0x3000, v29
	v_bitop3_b32 v29, v28, v0, 3 bitop3:0x78
	v_xor_b32_e32 v0, v0, v2
	v_lshl_or_b32 v209, v29, 3, v3
	v_bitop3_b32 v29, v187, v28, 4 bitop3:0x36
	v_lshlrev_b32_e32 v0, 4, v0
	v_lshl_or_b32 v210, v29, 3, v3
	v_bitop3_b32 v29, v187, v28, 8 bitop3:0x36
	v_bitop3_b32 v28, v187, v28, 12 bitop3:0x36
	v_and_b32_e32 v0, 48, v0
	v_lshlrev_b32_e32 v2, 6, v186
	s_movk_i32 s8, 0x2000
	v_lshl_or_b32 v211, v29, 3, v3
	v_lshl_or_b32 v212, v28, 3, v3
	v_or3_b32 v215, v0, v2, s8
	v_mov_b32_e32 v2, v1
	v_mov_b32_e32 v3, v1
	v_mov_b32_e32 v0, v1
	v_mov_b64_e32 v[30:31], v[2:3]
	v_mov_b64_e32 v[34:35], v[2:3]
	v_mov_b64_e32 v[38:39], v[2:3]
	v_mov_b64_e32 v[42:43], v[2:3]
	v_mov_b64_e32 v[46:47], v[2:3]
	v_mov_b64_e32 v[50:51], v[2:3]
	v_mov_b64_e32 v[54:55], v[2:3]
	v_mov_b64_e32 v[58:59], v[2:3]
	s_mov_b32 s9, 0
	v_mov_b32_e32 v108, 0
	v_mov_b64_e32 v[28:29], v[0:1]
	v_mov_b64_e32 v[32:33], v[0:1]
	v_mov_b64_e32 v[36:37], v[0:1]
	v_mov_b64_e32 v[40:41], v[0:1]
	v_mov_b64_e32 v[44:45], v[0:1]
	v_mov_b64_e32 v[48:49], v[0:1]
	v_mov_b64_e32 v[52:53], v[0:1]
	v_mov_b64_e32 v[56:57], v[0:1]
	v_mov_b32_e32 v109, 0
	v_mov_b32_e32 v110, 0
	v_mov_b32_e32 v111, 0
	s_xor_b64 exec, exec, s[2:3]
	s_cbranch_execz .LBB0_2311
; template <int DK, int QB, bool NA>
; DEVI void attn_item(const AttnArgs& a, unsigned char* smem) {
;     ...
;         k1[0] = ldsr<0>(a1); k1[1] = ldsr<2048>(a1); k1[2] = ldsr<4096>(a1); k1[3] = ldsr<6144>(a1);
;         if constexpr (KS == 3) { k2[0] = ldsr<0>(a2); k2[1] = ldsr<1024>(a2); k2[2] = ldsr<2048>(a2); k2[3] = ldsr<3072>(a2); }
;         if constexpr (KS == 3) asm volatile("s_waitcnt lgkmcnt(8)" : "+v"(k0[0]), "+v"(k0[1]), "+v"(k0[2]), "+v"(k0[3]) :: "memory");
;         else                   asm volatile("s_waitcnt lgkmcnt(4)" : "+v"(k0[0]), "+v"(k0[1]), "+v"(k0[2]), "+v"(k0[3]) :: "memory");
;         __builtin_amdgcn_sched_barrier(0);
; #pragma unroll
;         for (int kb = 0; kb < 4; ++kb)
; #pragma unroll
;           for (int qb = 0; qb < QB; ++qb) s[kb][qb] = __builtin_amdgcn_mfma_f32_16x16x32_bf16(k0[kb], qf[qb][0], s[kb][qb], 0, 0, 0);
;         if constexpr (KS == 3) asm volatile("s_waitcnt lgkmcnt(4)" : "+v"(k1[0]), "+v"(k1[1]), "+v"(k1[2]), "+v"(k1[3]) :: "memory");
;         else                   asm volatile("s_waitcnt lgkmcnt(0)" : "+v"(k1[0]), "+v"(k1[1]), "+v"(k1[2]), "+v"(k1[3]) :: "memory");
;         __builtin_amdgcn_sched_barrier(0);
; #pragma unroll
;         for (int kb = 0; kb < 4; ++kb)
; #pragma unroll
;           for (int qb = 0; qb < QB; ++qb) s[kb][qb] = __builtin_amdgcn_mfma_f32_16x16x32_bf16(k1[kb], qf[qb][1], s[kb][qb], 0, 0, 0);
;         if constexpr (KS == 3) {
;           asm volatile("s_waitcnt lgkmcnt(0)" : "+v"(k2[0]), "+v"(k2[1]), "+v"(k2[2]), "+v"(k2[3]) :: "memory");
;           __builtin_amdgcn_sched_barrier(0);
; #pragma unroll
;           for (int kb = 0; kb < 4; ++kb)
; #pragma unroll
;             for (int qb = 0; qb < QB; ++qb) s[kb][qb] = __builtin_amdgcn_mfma_f32_16x16x32_bf16(k2[kb], qf[qb][2], s[kb][qb], 0, 0, 0);
;     ...
;           const f32x2 scv = {a.sc2, a.sc2}, nmv = {-m[qb], -m[qb]};
;           f32x2 t[4][2];
; #pragma unroll
;           for (int kb = 0; kb < 4; ++kb)
; #pragma unroll
;             for (int h = 0; h < 2; ++h) {
;               const f32x2 sv = {s[kb][qb][2 * h], s[kb][qb][2 * h + 1]};
;               t[kb][h] = sv * scv + nmv;
;             }
;           float mx = fmaxf(t[0][0].x, t[0][0].y);
; #pragma unroll
;           for (int kb = 0; kb < 4; ++kb)
; #pragma unroll
;             for (int h = 0; h < 2; ++h) mx = fmaxf(mx, fmaxf(t[kb][h].x, t[kb][h].y));
	ds_read_b128 v[28:31], v213 offset:0
	ds_read_b128 v[32:35], v213 offset:0x800
	ds_read_b128 v[36:39], v213 offset:0x1000
	ds_read_b128 v[40:43], v213 offset:0x1800
	ds_read_b128 v[44:47], v214 offset:0
	ds_read_b128 v[48:51], v214 offset:0x800
	ds_read_b128 v[52:55], v214 offset:0x1000
	ds_read_b128 v[56:59], v214 offset:0x1800
	ds_read_b128 v[60:63], v215 offset:0
	ds_read_b128 v[64:67], v215 offset:0x400
	ds_read_b128 v[76:79], v215 offset:0x800
	ds_read_b128 v[80:83], v215 offset:0xc00
	s_nop 0
	s_waitcnt lgkmcnt(8)
	s_waitcnt vmcnt(0)
	s_setprio 1
	v_mfma_f32_16x16x32_bf16 v[68:71], v[28:31], v[24:27], 0
	s_waitcnt lgkmcnt(4)
	v_mfma_f32_16x16x32_bf16 v[28:31], v[28:31], v[20:23], 0
	v_mfma_f32_16x16x32_bf16 v[72:75], v[32:35], v[24:27], 0
	v_mfma_f32_16x16x32_bf16 v[32:35], v[32:35], v[20:23], 0
	v_mfma_f32_16x16x32_bf16 v[84:87], v[36:39], v[24:27], 0
	v_mfma_f32_16x16x32_bf16 v[36:39], v[36:39], v[20:23], 0
	v_mfma_f32_16x16x32_bf16 v[88:91], v[40:43], v[24:27], 0
	v_mfma_f32_16x16x32_bf16 v[40:43], v[40:43], v[20:23], 0
	v_mfma_f32_16x16x32_bf16 v[68:71], v[44:47], v[16:19], v[68:71]
	s_waitcnt lgkmcnt(0)
	v_mfma_f32_16x16x32_bf16 v[28:31], v[44:47], v[12:15], v[28:31]
	v_mfma_f32_16x16x32_bf16 v[44:47], v[48:51], v[16:19], v[72:75]
	v_mfma_f32_16x16x32_bf16 v[32:35], v[48:51], v[12:15], v[32:35]
	v_mfma_f32_16x16x32_bf16 v[48:51], v[52:55], v[16:19], v[84:87]
	v_mfma_f32_16x16x32_bf16 v[36:39], v[52:55], v[12:15], v[36:39]
	v_mfma_f32_16x16x32_bf16 v[52:55], v[56:59], v[16:19], v[88:91]
	v_mfma_f32_16x16x32_bf16 v[40:43], v[56:59], v[12:15], v[40:43]
	v_mfma_f32_16x16x32_bf16 v[84:87], v[60:63], v[8:11], v[68:71]
	ds_read_b64 v[56:57], v209 offset:0
	ds_read_b64 v[58:59], v210 offset:0
	v_mfma_f32_16x16x32_bf16 v[68:71], v[60:63], v[4:7], v[28:31]
	v_mfma_f32_16x16x32_bf16 v[60:63], v[64:67], v[8:11], v[44:47]
	s_nop 5
	v_mul_f32_e64 v92, v86, s34
	v_mul_f32_e64 v93, v87, s34
	v_pk_mul_f32 v[2:3], v[84:85], s[34:35] op_sel_hi:[1,0]
	v_max_f32_e32 v0, v92, v93
	v_mfma_f32_16x16x32_bf16 v[72:75], v[64:67], v[4:7], v[32:35]
	v_max3_f32 v0, v2, v3, v0
	v_pk_mul_f32 v[2:3], v[60:61], s[34:35] op_sel_hi:[1,0]
	v_mfma_f32_16x16x32_bf16 v[64:67], v[76:79], v[8:11], v[48:51]
	v_max_f32_e32 v92, v2, v3
	v_pk_mul_f32 v[2:3], v[62:63], s[34:35] op_sel_hi:[1,0]
	v_mfma_f32_16x16x32_bf16 v[88:91], v[80:83], v[8:11], v[52:55]
	v_max_f32_e32 v2, v2, v3
	v_max3_f32 v0, v0, v92, v2
	s_nop 2
	v_pk_mul_f32 v[2:3], v[64:65], s[34:35] op_sel_hi:[1,0]
	v_mfma_f32_16x16x32_bf16 v[76:79], v[76:79], v[4:7], v[36:39]
	v_max_f32_e32 v92, v2, v3
	v_pk_mul_f32 v[2:3], v[66:67], s[34:35] op_sel_hi:[1,0]
	ds_read_b64 v[52:53], v209 offset:0x800
	v_mfma_f32_16x16x32_bf16 v[80:83], v[80:83], v[4:7], v[40:43]
	s_setprio 0
	v_max_f32_e32 v2, v2, v3
	v_max3_f32 v0, v0, v92, v2
	v_pk_mul_f32 v[2:3], v[88:89], s[34:35] op_sel_hi:[1,0]
	ds_read_b64 v[54:55], v210 offset:0x800
	ds_read_b64 v[48:49], v209 offset:0x1000
	ds_read_b64 v[50:51], v210 offset:0x1000
	ds_read_b64 v[44:45], v209 offset:0x1800
	ds_read_b64 v[46:47], v210 offset:0x1800
	s_nop 0
	v_max_f32_e32 v92, v2, v3
	v_pk_mul_f32 v[2:3], v[90:91], s[34:35] op_sel_hi:[1,0]
	ds_read_b64 v[40:41], v211 offset:0
	ds_read_b64 v[42:43], v212 offset:0
	ds_read_b64 v[36:37], v211 offset:0x800
	ds_read_b64 v[38:39], v212 offset:0x800
	ds_read_b64 v[32:33], v211 offset:0x1000
	s_nop 0
	v_max_f32_e32 v2, v2, v3
	v_max3_f32 v0, v0, v92, v2
	v_mov_b32_e32 v2, v0
	s_nop 1
	v_permlane16_swap_b32_e32 v0, v2
	v_max_f32_e32 v2, v2, v2
	v_max_f32_e32 v0, v0, v0
	v_max_f32_e32 v0, v0, v2
	v_mov_b32_e32 v2, v0
	s_nop 1
	v_permlane32_swap_b32_e32 v0, v2
	v_max_f32_e32 v2, v2, v2
	v_max_f32_e32 v0, v0, v0
	v_max_f32_e32 v92, v0, v2
	v_fma_f32 v94, v62, s34, -v92
	v_fma_f32 v95, v63, s34, -v92
	v_fma_f32 v62, v60, s34, -v92
	v_fma_f32 v63, v61, s34, -v92
	v_fma_f32 v60, v84, s34, -v92
	v_fma_f32 v61, v85, s34, -v92
	v_fma_f32 v86, v86, s34, -v92
	v_fma_f32 v87, v87, s34, -v92
	v_exp_f32_e32 v60, v60
	v_exp_f32_e32 v61, v61
	v_exp_f32_e32 v86, v86
	v_exp_f32_e32 v87, v87
	v_exp_f32_e32 v62, v62
	v_add_f32_e32 v84, 0, v60
	v_add_f32_e32 v85, 0, v61
	v_exp_f32_e32 v63, v63
	v_fma_f32 v64, v64, s34, -v92
	v_fma_f32 v65, v65, s34, -v92
	v_cvt_pk_bf16_f32 v60, v60, v61
	v_add_f32_e32 v84, v86, v84
	v_add_f32_e32 v85, v87, v85
	v_cvt_pk_bf16_f32 v61, v86, v87
	v_exp_f32_e32 v86, v94
	v_exp_f32_e32 v87, v95
	v_fma_f32 v66, v66, s34, -v92
	v_fma_f32 v67, v67, s34, -v92
	v_exp_f32_e32 v64, v64
	v_exp_f32_e32 v65, v65
	v_exp_f32_e32 v66, v66
	v_exp_f32_e32 v67, v67
	v_add_f32_e32 v84, v62, v84
	v_add_f32_e32 v85, v63, v85
	v_fma_f32 v88, v88, s34, -v92
	v_fma_f32 v89, v89, s34, -v92
	v_add_f32_e32 v84, v86, v84
	v_add_f32_e32 v85, v87, v85
	v_fma_f32 v90, v90, s34, -v92
	v_fma_f32 v91, v91, s34, -v92
	v_add_f32_e32 v84, v64, v84
	v_add_f32_e32 v85, v65, v85
	v_cvt_pk_bf16_f32 v64, v64, v65
	v_add_f32_e32 v84, v66, v84
	v_add_f32_e32 v85, v67, v85
	v_cvt_pk_bf16_f32 v65, v66, v67
	v_exp_f32_e32 v66, v88
	v_exp_f32_e32 v67, v89
	v_cvt_pk_bf16_f32 v62, v62, v63
	v_cvt_pk_bf16_f32 v63, v86, v87
	v_exp_f32_e32 v86, v90
	v_exp_f32_e32 v87, v91
	v_add_f32_e32 v84, v66, v84
	v_add_f32_e32 v85, v67, v85
	v_pk_mul_f32 v[88:89], v[70:71], s[34:35] op_sel_hi:[1,0]
	v_cvt_pk_bf16_f32 v66, v66, v67
	v_add_f32_e32 v84, v86, v84
	v_add_f32_e32 v85, v87, v85
	v_cvt_pk_bf16_f32 v67, v86, v87
	v_pk_mul_f32 v[86:87], v[68:69], s[34:35] op_sel_hi:[1,0]
	v_max_f32_e32 v0, v88, v89
	v_max3_f32 v0, v86, v87, v0
	v_pk_mul_f32 v[86:87], v[72:73], s[34:35] op_sel_hi:[1,0]
	v_exp_f32_e64 v3, -v92
	v_max_f32_e32 v2, v86, v87
	v_pk_mul_f32 v[86:87], v[74:75], s[34:35] op_sel_hi:[1,0]
	ds_read_b64 v[34:35], v212 offset:0x1000
	ds_read_b64 v[28:29], v211 offset:0x1800
	ds_read_b64 v[30:31], v212 offset:0x1800
	s_nop 0
	v_max_f32_e32 v86, v86, v87
	v_max3_f32 v0, v0, v2, v86
	v_pk_mul_f32 v[86:87], v[76:77], s[34:35] op_sel_hi:[1,0]
	s_waitcnt lgkmcnt(0)
; template <int DK, int QB, bool NA>
; DEVI void attn_item(const AttnArgs& a, unsigned char* smem) {
;     ...
;           float mx = fmaxf(t[0][0].x, t[0][0].y);
; #pragma unroll
;           for (int kb = 0; kb < 4; ++kb)
; #pragma unroll
;             for (int h = 0; h < 2; ++h) mx = fmaxf(mx, fmaxf(t[kb][h].x, t[kb][h].y));
;           if (j == 0 || __any(mx > 6.f)) {
;             mx = xmax32(xmax16(mx));
;             const float d = (j == 0) ? mx : fmaxf(mx, 0.f);
;             const float alpha = __builtin_amdgcn_exp2f(-d);
;             const f32x2 dv = {d, d};
; #pragma unroll
;             for (int kb = 0; kb < 4; ++kb)
; #pragma unroll
;               for (int h = 0; h < 2; ++h) t[kb][h] -= dv;
;             m[qb] += d;
;             l[qb] *= alpha;
; #pragma unroll
;             for (int db = 0; db < 4; ++db) o[db][qb] *= alpha;
;           }
;           f32x2 ls2 = {0.f, 0.f};
;           unsigned pw[2][4];
; #pragma unroll
;           for (int kb = 0; kb < 4; ++kb)
; #pragma unroll
;             for (int h = 0; h < 2; ++h) {
;               const f32x2 pe = {__builtin_amdgcn_exp2f(t[kb][h].x), __builtin_amdgcn_exp2f(t[kb][h].y)};
;               ls2 += pe;
;               pw[kb >> 1][(kb & 1) * 2 + h] = pk2(pe.x, pe.y);
;             }
;           l[qb] += ls2.x + ls2.y;
; #pragma unroll
;           for (int c = 0; c < 2; ++c) {
;             const u32x4 pv = (u32x4){pw[c][0], pw[c][1], pw[c][2], pw[c][3]};
;             pf[qb][c] = __builtin_bit_cast(bf16x8, pv);
;           }
;     ...
;       asm volatile("s_waitcnt lgkmcnt(0)"
;                    : "+v"(va[0][0]), "+v"(va[0][1]), "+v"(va[0][2]), "+v"(va[0][3]), "+v"(va[1][0]), "+v"(va[1][1]), "+v"(va[1][2]), "+v"(va[1][3]),
;                      "+v"(vbq[0][0]), "+v"(vbq[0][1]), "+v"(vbq[0][2]), "+v"(vbq[0][3]), "+v"(vbq[1][0]), "+v"(vbq[1][1]), "+v"(vbq[1][2]), "+v"(vbq[1][3])
;                    :: "memory");
;       __builtin_amdgcn_sched_barrier(0);
; #pragma unroll
;       for (int c = 0; c < 2; ++c)
; #pragma unroll
;         for (int db = 0; db < 4; ++db) {
;           const u32x4 vw = (u32x4){va[c][db].x, va[c][db].y, vbq[c][db].x, vbq[c][db].y};
;           const bf16x8 vf = __builtin_bit_cast(bf16x8, vw);
; #pragma unroll
;           for (int qb = 0; qb < QB; ++qb) o[db][qb] = __builtin_amdgcn_mfma_f32_16x16x32_bf16(vf, pf[qb][c], o[db][qb], 0, 0, 0);
;         }
	s_nop 0
	v_max_f32_e32 v2, v86, v87
	v_pk_mul_f32 v[86:87], v[78:79], s[34:35] op_sel_hi:[1,0]
	s_nop 0
	v_max_f32_e32 v86, v86, v87
	v_max3_f32 v0, v0, v2, v86
	v_pk_mul_f32 v[86:87], v[80:81], s[34:35] op_sel_hi:[1,0]
	s_nop 0
	v_max_f32_e32 v2, v86, v87
	v_pk_mul_f32 v[86:87], v[82:83], s[34:35] op_sel_hi:[1,0]
	s_nop 0
	v_max_f32_e32 v86, v86, v87
	v_max3_f32 v0, v0, v2, v86
	v_mov_b32_e32 v2, v0
	s_nop 1
	v_permlane16_swap_b32_e32 v0, v2
	v_max_f32_e32 v2, v2, v2
	v_max_f32_e32 v0, v0, v0
	v_max_f32_e32 v0, v0, v2
	v_mov_b32_e32 v2, v0
	s_nop 1
	v_permlane32_swap_b32_e32 v0, v2
	v_max_f32_e32 v2, v2, v2
	v_max_f32_e32 v0, v0, v0
	v_max_f32_e32 v93, v0, v2
	v_mov_b32_e32 v0, v93
	v_fma_f32 v68, v68, s34, -v0
	v_fma_f32 v69, v69, s34, -v0
	v_fma_f32 v70, v70, s34, -v0
	v_fma_f32 v71, v71, s34, -v0
	v_exp_f32_e32 v68, v68
	v_exp_f32_e32 v69, v69
	v_exp_f32_e32 v70, v70
	v_exp_f32_e32 v71, v71
	v_fma_f32 v72, v72, s34, -v0
	v_fma_f32 v73, v73, s34, -v0
	v_add_f32_e32 v86, 0, v68
	v_add_f32_e32 v87, 0, v69
	v_fma_f32 v74, v74, s34, -v0
	v_fma_f32 v75, v75, s34, -v0
	v_cvt_pk_bf16_f32 v68, v68, v69
	v_add_f32_e32 v86, v70, v86
	v_add_f32_e32 v87, v71, v87
	v_cvt_pk_bf16_f32 v69, v70, v71
	v_exp_f32_e32 v70, v72
	v_exp_f32_e32 v71, v73
	v_exp_f32_e32 v74, v74
	v_exp_f32_e32 v75, v75
	v_fma_f32 v76, v76, s34, -v0
	v_fma_f32 v77, v77, s34, -v0
	v_add_f32_e32 v72, v70, v86
	v_add_f32_e32 v73, v71, v87
	v_cvt_pk_bf16_f32 v70, v70, v71
	v_add_f32_e32 v72, v74, v72
	v_add_f32_e32 v73, v75, v73
	v_cvt_pk_bf16_f32 v71, v74, v75
	v_exp_f32_e32 v74, v76
	v_exp_f32_e32 v75, v77
	v_fma_f32 v78, v78, s34, -v0
	v_fma_f32 v79, v79, s34, -v0
	v_fma_f32 v80, v80, s34, -v0
	v_fma_f32 v81, v81, s34, -v0
	v_fma_f32 v82, v82, s34, -v0
	v_fma_f32 v83, v83, s34, -v0
	v_add_f32_e32 v76, v74, v72
	v_add_f32_e32 v77, v75, v73
	v_cvt_pk_bf16_f32 v72, v74, v75
	v_exp_f32_e32 v74, v78
	v_exp_f32_e32 v75, v79
	v_exp_f32_e32 v78, v82
	v_exp_f32_e32 v79, v83
	v_exp_f32_e64 v2, -v93
	v_add_f32_e32 v76, v74, v76
	v_add_f32_e32 v77, v75, v77
	v_cvt_pk_bf16_f32 v73, v74, v75
	v_exp_f32_e32 v74, v80
	v_exp_f32_e32 v75, v81
	v_add_f32_e32 v110, 0, v92
	v_add_f32_e32 v111, 0, v93
	v_add_f32_e32 v76, v74, v76
	v_add_f32_e32 v77, v75, v77
	s_nop 0
	v_add_f32_e32 v86, v78, v76
	v_add_f32_e32 v87, v79, v77
	v_cvt_pk_bf16_f32 v74, v74, v75
	v_cvt_pk_bf16_f32 v75, v78, v79
	v_mov_b32_e32 v78, v86
	v_mov_b32_e32 v79, v84
	v_mov_b32_e32 v84, v87
	v_add_f32_e32 v84, v78, v84
	v_add_f32_e32 v85, v79, v85
	v_pk_mul_f32 v[76:77], v[2:3], 0 op_sel_hi:[1,0]
	v_pk_fma_f32 v[108:109], v[2:3], 0, v[84:85] op_sel_hi:[1,0,1]
	v_mov_b32_e32 v80, v77
	v_mov_b32_e32 v81, v77
	v_mov_b32_e32 v82, v77
	v_mov_b32_e32 v83, v77
	v_mov_b32_e32 v77, v76
	v_mov_b32_e32 v78, v76
	v_mov_b32_e32 v79, v76
	s_setprio 1
	v_mfma_f32_16x16x32_bf16 v[84:87], v[56:59], v[60:63], v[80:83]
	s_nop 0
	v_mfma_f32_16x16x32_bf16 v[88:91], v[56:59], v[68:71], v[76:79]
	v_mfma_f32_16x16x32_bf16 v[92:95], v[52:55], v[60:63], v[80:83]
	v_mfma_f32_16x16x32_bf16 v[96:99], v[52:55], v[68:71], v[76:79]
	v_mfma_f32_16x16x32_bf16 v[100:103], v[48:51], v[60:63], v[80:83]
	v_mfma_f32_16x16x32_bf16 v[104:107], v[48:51], v[68:71], v[76:79]
	v_mfma_f32_16x16x32_bf16 v[60:63], v[44:47], v[60:63], v[80:83]
	v_mfma_f32_16x16x32_bf16 v[68:71], v[44:47], v[68:71], v[76:79]
	v_mfma_f32_16x16x32_bf16 v[56:59], v[40:43], v[64:67], v[84:87]
	v_mfma_f32_16x16x32_bf16 v[52:55], v[40:43], v[72:75], v[88:91]
	v_mfma_f32_16x16x32_bf16 v[48:51], v[36:39], v[64:67], v[92:95]
	v_mfma_f32_16x16x32_bf16 v[44:47], v[36:39], v[72:75], v[96:99]
	v_mfma_f32_16x16x32_bf16 v[40:43], v[32:35], v[64:67], v[100:103]
	v_mfma_f32_16x16x32_bf16 v[36:39], v[32:35], v[72:75], v[104:107]
	v_mfma_f32_16x16x32_bf16 v[32:35], v[28:31], v[64:67], v[60:63]
	v_mfma_f32_16x16x32_bf16 v[28:31], v[28:31], v[72:75], v[68:71]
	s_setprio 0

; DEVI unsigned pk2(float lo, float hi) { const f32x2_t v = {lo, hi}; const bf16x2_t b = __builtin_convertvector(v, bf16x2_t); return __builtin_bit_cast(unsigned, b); }
; template <int DK, int QB, bool NA>
; DEVI void attn_item(const AttnArgs& a, unsigned char* smem) {
;     ...
;           f32x2 ls2 = {0.f, 0.f};
;           unsigned pw[2][4];
; #pragma unroll
;           for (int kb = 0; kb < 4; ++kb)
; #pragma unroll
;             for (int h = 0; h < 2; ++h) {
;               const f32x2 pe = {__builtin_amdgcn_exp2f(t[kb][h].x), __builtin_amdgcn_exp2f(t[kb][h].y)};
;               ls2 += pe;
;               pw[kb >> 1][(kb & 1) * 2 + h] = pk2(pe.x, pe.y);
;             }
;           l[qb] += ls2.x + ls2.y;
; #pragma unroll
;           for (int c = 0; c < 2; ++c) {
;             const u32x4 pv = (u32x4){pw[c][0], pw[c][1], pw[c][2], pw[c][3]};
;             pf[qb][c] = __builtin_bit_cast(bf16x8, pv);
;           }
;     ...
; #pragma unroll
;       for (int c = 0; c < 2; ++c)
; #pragma unroll
;         for (int db = 0; db < 4; ++db) {
;           const u32x4 vw = (u32x4){va[c][db].x, va[c][db].y, vbq[c][db].x, vbq[c][db].y};
;           const bf16x8 vf = __builtin_bit_cast(bf16x8, vw);
; #pragma unroll
;           for (int qb = 0; qb < QB; ++qb) o[db][qb] = __builtin_amdgcn_mfma_f32_16x16x32_bf16(vf, pf[qb][c], o[db][qb], 0, 0, 0);
;         }
.LBB0_2312:
	v_exp_f32_e32 v94, v182
	v_exp_f32_e32 v95, v183
	v_exp_f32_e32 v182, v180
	v_exp_f32_e32 v183, v181
	v_exp_f32_e32 v126, v126
	v_exp_f32_e32 v127, v127
	v_add_f32_e32 v218, 0, v94
	v_add_f32_e32 v219, 0, v95
	v_exp_f32_e32 v128, v128
	v_exp_f32_e32 v129, v129
	v_cvt_pk_bf16_f32 v180, v94, v95
	v_add_f32_e32 v94, v182, v218
	v_add_f32_e32 v95, v183, v219
	v_exp_f32_e32 v124, v124
	v_exp_f32_e32 v125, v125
	v_cvt_pk_bf16_f32 v181, v182, v183
	v_add_f32_e32 v94, v126, v94
	v_add_f32_e32 v95, v127, v95
	v_cvt_pk_bf16_f32 v182, v126, v127
	v_exp_f32_e32 v126, v122
	v_exp_f32_e32 v127, v123
	v_exp_f32_e32 v120, v120
	v_exp_f32_e32 v121, v121
	v_add_f32_e32 v94, v128, v94
	v_add_f32_e32 v95, v129, v95
	v_exp_f32_e32 v2, v2
	v_exp_f32_e32 v3, v3
	v_add_f32_e32 v94, v124, v94
	v_add_f32_e32 v95, v125, v95
	v_cvt_pk_bf16_f32 v122, v124, v125
	v_add_f32_e32 v94, v126, v94
	v_add_f32_e32 v95, v127, v95
	v_cvt_pk_bf16_f32 v125, v2, v3
	v_add_f32_e32 v94, v120, v94
	v_add_f32_e32 v95, v121, v95
	v_exp_f32_e32 v104, v104
	v_add_f32_e32 v94, v2, v94
	v_add_f32_e32 v95, v3, v95
	v_exp_f32_e32 v2, v184
	v_exp_f32_e32 v3, v185
	v_add_f32_e32 v0, v94, v95
	v_exp_f32_e32 v94, v106
	v_exp_f32_e32 v95, v107
	v_exp_f32_e32 v105, v105
	v_add_f32_e32 v106, 0, v2
	v_add_f32_e32 v107, 0, v3
	v_exp_f32_e32 v102, v102
	v_exp_f32_e32 v103, v103
	v_cvt_pk_bf16_f32 v123, v126, v127
	v_cvt_pk_bf16_f32 v126, v2, v3
	v_add_f32_e32 v2, v94, v106
	v_add_f32_e32 v3, v95, v107
	v_cvt_pk_bf16_f32 v127, v94, v95
	v_exp_f32_e32 v94, v100
	v_exp_f32_e32 v95, v101
	v_exp_f32_e32 v98, v98
	v_exp_f32_e32 v99, v99
	v_add_f32_e32 v2, v104, v2
	v_add_f32_e32 v3, v105, v3
	v_exp_f32_e32 v96, v96
	v_exp_f32_e32 v97, v97
	v_add_f32_e32 v2, v102, v2
	v_add_f32_e32 v3, v103, v3
	v_exp_f32_e32 v92, v92
	v_exp_f32_e32 v93, v93
	v_add_f32_e32 v2, v94, v2
	v_add_f32_e32 v3, v95, v3
	s_waitcnt lgkmcnt(0)
	v_add_f32_e32 v109, v109, v0
	v_add_f32_e32 v2, v98, v2
	v_add_f32_e32 v3, v99, v3
	v_cvt_pk_bf16_f32 v183, v128, v129
	v_add_f32_e32 v2, v96, v2
	v_add_f32_e32 v3, v97, v3
	v_cvt_pk_bf16_f32 v124, v120, v121
	v_add_f32_e32 v2, v92, v2
	v_add_f32_e32 v3, v93, v3
	v_cvt_pk_bf16_f32 v128, v104, v105
	v_add_f32_e32 v0, v2, v3
	v_add_f32_e32 v108, v108, v0
	v_cvt_pk_bf16_f32 v129, v102, v103
	v_cvt_pk_bf16_f32 v94, v94, v95
	v_cvt_pk_bf16_f32 v95, v98, v99
	v_cvt_pk_bf16_f32 v96, v96, v97
	v_cvt_pk_bf16_f32 v97, v92, v93
	s_setprio 1
	v_mfma_f32_16x16x32_bf16 v[56:59], v[88:91], v[180:183], v[56:59]
	v_mfma_f32_16x16x32_bf16 v[52:55], v[88:91], v[126:129], v[52:55]
	v_mfma_f32_16x16x32_bf16 v[48:51], v[84:87], v[180:183], v[48:51]
	v_mfma_f32_16x16x32_bf16 v[44:47], v[84:87], v[126:129], v[44:47]
	v_mfma_f32_16x16x32_bf16 v[40:43], v[80:83], v[180:183], v[40:43]
	v_mfma_f32_16x16x32_bf16 v[36:39], v[80:83], v[126:129], v[36:39]
	v_mfma_f32_16x16x32_bf16 v[32:35], v[76:79], v[180:183], v[32:35]
	v_mfma_f32_16x16x32_bf16 v[28:31], v[76:79], v[126:129], v[28:31]
	v_mfma_f32_16x16x32_bf16 v[56:59], v[72:75], v[122:125], v[56:59]
	v_mfma_f32_16x16x32_bf16 v[52:55], v[72:75], v[94:97], v[52:55]
	v_mfma_f32_16x16x32_bf16 v[48:51], v[68:71], v[122:125], v[48:51]
	v_mfma_f32_16x16x32_bf16 v[44:47], v[68:71], v[94:97], v[44:47]
	v_mfma_f32_16x16x32_bf16 v[40:43], v[64:67], v[122:125], v[40:43]
	v_mfma_f32_16x16x32_bf16 v[36:39], v[64:67], v[94:97], v[36:39]
	v_mfma_f32_16x16x32_bf16 v[32:35], v[60:63], v[122:125], v[32:35]
	v_mfma_f32_16x16x32_bf16 v[28:31], v[60:63], v[94:97], v[28:31]
	s_setprio 0

; DEVI unsigned pk2(float lo, float hi) { const f32x2_t v = {lo, hi}; const bf16x2_t b = __builtin_convertvector(v, bf16x2_t); return __builtin_bit_cast(unsigned, b); }
; template <int DK, int QB, bool NA>
; DEVI void attn_item(const AttnArgs& a, unsigned char* smem) {
;     ...
;           f32x2 ls2 = {0.f, 0.f};
;           unsigned pw[2][4];
; #pragma unroll
;           for (int kb = 0; kb < 4; ++kb)
; #pragma unroll
;             for (int h = 0; h < 2; ++h) {
;               const f32x2 pe = {__builtin_amdgcn_exp2f(t[kb][h].x), __builtin_amdgcn_exp2f(t[kb][h].y)};
;               ls2 += pe;
;               pw[kb >> 1][(kb & 1) * 2 + h] = pk2(pe.x, pe.y);
;             }
;           l[qb] += ls2.x + ls2.y;
; #pragma unroll
;           for (int c = 0; c < 2; ++c) {
;             const u32x4 pv = (u32x4){pw[c][0], pw[c][1], pw[c][2], pw[c][3]};
;             pf[qb][c] = __builtin_bit_cast(bf16x8, pv);
;           }
;     ...
; #pragma unroll
;       for (int c = 0; c < 2; ++c)
; #pragma unroll
;         for (int db = 0; db < 4; ++db) {
;           const u32x4 vw = (u32x4){va[c][db].x, va[c][db].y, vbq[c][db].x, vbq[c][db].y};
;           const bf16x8 vf = __builtin_bit_cast(bf16x8, vw);
; #pragma unroll
;           for (int qb = 0; qb < QB; ++qb) o[db][qb] = __builtin_amdgcn_mfma_f32_16x16x32_bf16(vf, pf[qb][c], o[db][qb], 0, 0, 0);
;         }
.LBB0_2326:
	v_exp_f32_e32 v94, v124
	v_exp_f32_e32 v95, v125
	v_exp_f32_e32 v124, v122
	v_exp_f32_e32 v125, v123
	v_exp_f32_e32 v118, v118
	v_exp_f32_e32 v119, v119
	v_add_f32_e32 v128, 0, v94
	v_add_f32_e32 v129, 0, v95
	v_exp_f32_e32 v120, v120
	v_exp_f32_e32 v121, v121
	v_cvt_pk_bf16_f32 v122, v94, v95
	v_add_f32_e32 v94, v124, v128
	v_add_f32_e32 v95, v125, v129
	v_exp_f32_e32 v116, v116
	v_exp_f32_e32 v117, v117
	v_cvt_pk_bf16_f32 v123, v124, v125
	v_add_f32_e32 v94, v118, v94
	v_add_f32_e32 v95, v119, v95
	v_cvt_pk_bf16_f32 v124, v118, v119
	v_exp_f32_e32 v118, v114
	v_exp_f32_e32 v119, v115
	v_exp_f32_e32 v112, v112
	v_exp_f32_e32 v113, v113
	v_add_f32_e32 v94, v120, v94
	v_add_f32_e32 v95, v121, v95
	v_exp_f32_e32 v2, v2
	v_exp_f32_e32 v3, v3
	v_add_f32_e32 v94, v116, v94
	v_add_f32_e32 v95, v117, v95
	v_cvt_pk_bf16_f32 v114, v116, v117
	v_add_f32_e32 v94, v118, v94
	v_add_f32_e32 v95, v119, v95
	v_cvt_pk_bf16_f32 v117, v2, v3
	v_add_f32_e32 v94, v112, v94
	v_add_f32_e32 v95, v113, v95
	v_exp_f32_e32 v104, v104
	v_add_f32_e32 v94, v2, v94
	v_add_f32_e32 v95, v3, v95
	v_exp_f32_e32 v2, v126
	v_exp_f32_e32 v3, v127
	v_add_f32_e32 v0, v94, v95
	v_exp_f32_e32 v94, v106
	v_exp_f32_e32 v95, v107
	v_exp_f32_e32 v105, v105
	v_add_f32_e32 v106, 0, v2
	v_add_f32_e32 v107, 0, v3
	v_exp_f32_e32 v102, v102
	v_exp_f32_e32 v103, v103
	v_cvt_pk_bf16_f32 v115, v118, v119
	v_cvt_pk_bf16_f32 v118, v2, v3
	v_add_f32_e32 v2, v94, v106
	v_add_f32_e32 v3, v95, v107
	v_cvt_pk_bf16_f32 v119, v94, v95
	v_exp_f32_e32 v94, v100
	v_exp_f32_e32 v95, v101
	v_exp_f32_e32 v98, v98
	v_exp_f32_e32 v99, v99
	v_add_f32_e32 v2, v104, v2
	v_add_f32_e32 v3, v105, v3
	v_exp_f32_e32 v96, v96
	v_exp_f32_e32 v97, v97
	v_add_f32_e32 v2, v102, v2
	v_add_f32_e32 v3, v103, v3
	v_exp_f32_e32 v92, v92
	v_exp_f32_e32 v93, v93
	v_add_f32_e32 v2, v94, v2
	v_add_f32_e32 v3, v95, v3
	s_waitcnt lgkmcnt(0)
	v_add_f32_e32 v109, v109, v0
	v_add_f32_e32 v2, v98, v2
	v_add_f32_e32 v3, v99, v3
	v_cvt_pk_bf16_f32 v125, v120, v121
	v_add_f32_e32 v2, v96, v2
	v_add_f32_e32 v3, v97, v3
	v_cvt_pk_bf16_f32 v116, v112, v113
	v_add_f32_e32 v2, v92, v2
	v_add_f32_e32 v3, v93, v3
	v_cvt_pk_bf16_f32 v120, v104, v105
	v_add_f32_e32 v0, v2, v3
	v_add_f32_e32 v108, v108, v0
	v_cvt_pk_bf16_f32 v121, v102, v103
	v_cvt_pk_bf16_f32 v94, v94, v95
	v_cvt_pk_bf16_f32 v95, v98, v99
	v_cvt_pk_bf16_f32 v96, v96, v97
	v_cvt_pk_bf16_f32 v97, v92, v93
	s_setprio 1
	v_mfma_f32_16x16x32_bf16 v[56:59], v[88:91], v[122:125], v[56:59]
	v_mfma_f32_16x16x32_bf16 v[52:55], v[88:91], v[118:121], v[52:55]
	v_mfma_f32_16x16x32_bf16 v[48:51], v[84:87], v[122:125], v[48:51]
	v_mfma_f32_16x16x32_bf16 v[44:47], v[84:87], v[118:121], v[44:47]
	v_mfma_f32_16x16x32_bf16 v[40:43], v[80:83], v[122:125], v[40:43]
	v_mfma_f32_16x16x32_bf16 v[36:39], v[80:83], v[118:121], v[36:39]
	v_mfma_f32_16x16x32_bf16 v[32:35], v[76:79], v[122:125], v[32:35]
	v_mfma_f32_16x16x32_bf16 v[28:31], v[76:79], v[118:121], v[28:31]
	v_mfma_f32_16x16x32_bf16 v[56:59], v[72:75], v[114:117], v[56:59]
	v_mfma_f32_16x16x32_bf16 v[52:55], v[72:75], v[94:97], v[52:55]
	v_mfma_f32_16x16x32_bf16 v[48:51], v[68:71], v[114:117], v[48:51]
	v_mfma_f32_16x16x32_bf16 v[44:47], v[68:71], v[94:97], v[44:47]
	v_mfma_f32_16x16x32_bf16 v[40:43], v[64:67], v[114:117], v[40:43]
	v_mfma_f32_16x16x32_bf16 v[36:39], v[64:67], v[94:97], v[36:39]
	v_mfma_f32_16x16x32_bf16 v[32:35], v[60:63], v[114:117], v[32:35]
	v_mfma_f32_16x16x32_bf16 v[28:31], v[60:63], v[94:97], v[28:31]
	s_setprio 0

; DEVI unsigned pk2(float lo, float hi) { const f32x2_t v = {lo, hi}; const bf16x2_t b = __builtin_convertvector(v, bf16x2_t); return __builtin_bit_cast(unsigned, b); }
; DEVI size_t blk_off(int row, int col) { return ((size_t)(col >> 5) * MROWS + row) * 32 + (col & 31); }
; DEVI float xsum16(float x) { auto r = __builtin_amdgcn_permlane16_swap(__float_as_uint(x), __float_as_uint(x), false, false); return __uint_as_float(r[0]) + __uint_as_float(r[1]); }
; DEVI float xsum32(float x) { auto r = __builtin_amdgcn_permlane32_swap(__float_as_uint(x), __float_as_uint(x), false, false); return __uint_as_float(r[0]) + __uint_as_float(r[1]); }
; template <int DK, int QB, bool NA>
; DEVI void attn_item(const AttnArgs& a, unsigned char* smem) {
;     ...
;           f32x2 ls2 = {0.f, 0.f};
;           unsigned pw[2][4];
; #pragma unroll
;           for (int kb = 0; kb < 4; ++kb)
; #pragma unroll
;             for (int h = 0; h < 2; ++h) {
;               const f32x2 pe = {__builtin_amdgcn_exp2f(t[kb][h].x), __builtin_amdgcn_exp2f(t[kb][h].y)};
;               ls2 += pe;
;               pw[kb >> 1][(kb & 1) * 2 + h] = pk2(pe.x, pe.y);
;             }
;           l[qb] += ls2.x + ls2.y;
; #pragma unroll
;           for (int c = 0; c < 2; ++c) {
;             const u32x4 pv = (u32x4){pw[c][0], pw[c][1], pw[c][2], pw[c][3]};
;             pf[qb][c] = __builtin_bit_cast(bf16x8, pv);
;           }
;     ...
;   if (wact) {
; #pragma unroll
;     for (int qb = 0; qb < QB; ++qb) {
;       const float lt = xsum32(xsum16(l[qb]));
;       const float inv = 1.0f / lt;
;       const int qi = w * QB * 16 + qb * 16 + l16;
;       if (qi < a.nq) {
; #pragma unroll
;         for (int db = 0; db < 4; ++db) {
;           const f32x4 v = o[db][qb] * inv;
;           *(u32x2*)(a.O + blk_off(a.orow0 + qi, a.ocol0 + db * 16 + g * 4)) = (u32x2){pk2(v[0], v[1]), pk2(v[2], v[3])};
;         }
;       }
.LBB0_2332:
	v_exp_f32_e32 v74, v74
	v_exp_f32_e32 v75, v75
	v_exp_f32_e32 v72, v72
	v_exp_f32_e32 v73, v73
	v_exp_f32_e32 v26, v26
	v_exp_f32_e32 v27, v27
	v_add_f32_e32 v80, 0, v74
	v_add_f32_e32 v81, 0, v75
	v_cvt_pk_bf16_f32 v78, v74, v75
	v_add_f32_e32 v74, v72, v80
	v_add_f32_e32 v75, v73, v81
	v_cvt_pk_bf16_f32 v79, v72, v73
	v_add_f32_e32 v72, v26, v74
	v_add_f32_e32 v73, v27, v75
	v_exp_f32_e32 v70, v70
	v_add_f32_e32 v72, v26, v72
	v_add_f32_e32 v73, v27, v73
	v_exp_f32_e32 v71, v71
	v_add_f32_e32 v72, v26, v72
	v_add_f32_e32 v73, v27, v73
	v_cvt_pk_bf16_f32 v80, v26, v27
	v_add_f32_e32 v72, v26, v72
	v_add_f32_e32 v73, v27, v73
	v_exp_f32_e32 v68, v68
	v_add_f32_e32 v72, v26, v72
	v_add_f32_e32 v73, v27, v73
	v_exp_f32_e32 v69, v69
	v_add_f32_e32 v26, v26, v72
	v_add_f32_e32 v27, v27, v73
	v_exp_f32_e32 v72, v76
	v_exp_f32_e32 v73, v77
	s_waitcnt lgkmcnt(0)
	v_add_f32_e32 v0, v26, v27
	v_add_f32_e32 v0, v109, v0
	v_cvt_pk_bf16_f32 v76, v70, v71
	v_mov_b32_e32 v81, v80
	v_mov_b32_e32 v82, v80
	v_mov_b32_e32 v83, v80
	v_mov_b32_e32 v84, v80
	v_mov_b32_e32 v85, v80
	v_cvt_pk_bf16_f32 v74, v68, v69
	v_cvt_pk_bf16_f32 v75, v72, v73
	v_mov_b32_e32 v77, v76
	v_mov_b32_e32 v86, v76
	v_mov_b32_e32 v87, v76
	v_mov_b32_e32 v88, v76
	v_mov_b32_e32 v89, v76
	s_setprio 1
	v_mfma_f32_16x16x32_bf16 v[56:59], v[64:67], v[78:81], v[56:59]
	s_mul_i32 s20, s58, 0x18500
	v_mfma_f32_16x16x32_bf16 v[52:55], v[64:67], v[74:77], v[52:55]
	v_mfma_f32_16x16x32_bf16 v[48:51], v[60:63], v[78:81], v[48:51]
	v_mfma_f32_16x16x32_bf16 v[44:47], v[60:63], v[74:77], v[44:47]
	v_mfma_f32_16x16x32_bf16 v[40:43], v[22:25], v[78:81], v[40:43]
	v_mfma_f32_16x16x32_bf16 v[22:25], v[22:25], v[74:77], v[36:39]
	v_mfma_f32_16x16x32_bf16 v[60:63], v[18:21], v[78:81], v[32:35]
	s_nop 1
	v_mov_b32_e32 v36, v0
	s_nop 1
	v_permlane16_swap_b32_e32 v0, v36
	v_mfma_f32_16x16x32_bf16 v[64:67], v[18:21], v[74:77], v[28:31]
	v_add_f32_e32 v36, v0, v36
	v_or_b32_e32 v35, v208, v186
	v_lshlrev_b32_e32 v34, 2, v187
	v_mfma_f32_16x16x32_bf16 v[30:33], v[14:17], v[82:85], v[56:59]
	v_mov_b32_e32 v37, v36
	s_nop 1
	v_permlane32_swap_b32_e32 v36, v37
	v_mfma_f32_16x16x32_bf16 v[14:17], v[14:17], v[86:89], v[52:55]
	v_cmp_gt_i32_e32 vcc, s57, v35
	v_lshlrev_b32_e32 v0, 1, v34
	v_mfma_f32_16x16x32_bf16 v[26:29], v[10:13], v[82:85], v[48:51]
	v_mfma_f32_16x16x32_bf16 v[10:13], v[10:13], v[86:89], v[44:47]
	v_mfma_f32_16x16x32_bf16 v[18:21], v[6:9], v[82:85], v[40:43]
	v_mfma_f32_16x16x32_bf16 v[6:9], v[6:9], v[86:89], v[22:25]
	v_mfma_f32_16x16x32_bf16 v[22:25], v[2:5], v[82:85], v[60:63]
	v_mfma_f32_16x16x32_bf16 v[2:5], v[2:5], v[86:89], v[64:67]
	s_setprio 0
	s_and_saveexec_b64 s[0:1], vcc
	s_cbranch_execz .LBB0_2334
	v_add_f32_e32 v36, v36, v37
	v_div_scale_f32 v37, s[8:9], v36, v36, 1.0
	v_rcp_f32_e32 v38, v37
	v_div_scale_f32 v39, vcc, 1.0, v36, 1.0
	s_add_i32 s8, s20, 0xc280
	v_fma_f32 v40, -v37, v38, 1.0
	v_fmac_f32_e32 v38, v40, v38
	v_mul_f32_e32 v40, v39, v38
	v_fma_f32 v41, -v37, v40, v39
	v_fmac_f32_e32 v40, v41, v38
	v_fma_f32 v37, -v37, v40, v39
	v_div_fmas_f32 v37, v37, v38, v40
	v_div_fixup_f32 v36, v37, v36, 1.0
	v_pk_mul_f32 v[32:33], v[32:33], v[36:37] op_sel_hi:[1,0]
	v_pk_mul_f32 v[30:31], v[30:31], v[36:37] op_sel_hi:[1,0]
	v_pk_mul_f32 v[20:21], v[20:21], v[36:37] op_sel_hi:[1,0]
	v_cvt_pk_bf16_f32 v30, v30, v31
	v_cvt_pk_bf16_f32 v31, v32, v33
	v_add_u32_e32 v32, s59, v35
	v_ashrrev_i32_e32 v33, 31, v32
	v_pk_mul_f32 v[18:19], v[18:19], v[36:37] op_sel_hi:[1,0]
	s_mov_b32 s9, s21
	v_readlane_b32 s28, v251, 54
	v_cvt_pk_bf16_f32 v18, v18, v19
	v_cvt_pk_bf16_f32 v19, v20, v21
	v_lshl_add_u64 v[20:21], v[32:33], 0, s[8:9]
	v_readlane_b32 s29, v251, 55
	v_lshlrev_b64 v[20:21], 6, v[20:21]
	v_lshl_add_u64 v[38:39], v[32:33], 0, s[20:21]
	v_lshl_add_u64 v[20:21], s[28:29], 0, v[20:21]
	v_lshl_add_u64 v[20:21], v[20:21], 0, v[0:1]
	global_store_dwordx2 v[20:21], v[18:19], off
	v_pk_mul_f32 v[18:19], v[24:25], v[36:37] op_sel_hi:[1,0]
	v_pk_mul_f32 v[20:21], v[22:23], v[36:37] op_sel_hi:[1,0]
	v_or_b32_e32 v22, s56, v34
	v_cvt_pk_bf16_f32 v20, v20, v21
	v_cvt_pk_bf16_f32 v21, v18, v19
	v_or_b32_e32 v18, 48, v22
	v_lshrrev_b32_e32 v18, 5, v18
	v_mul_lo_u32 v18, v18, s93
	v_mov_b32_e32 v19, v1
	v_lshl_add_u64 v[18:19], v[18:19], 0, v[32:33]
	v_lshlrev_b64 v[38:39], 6, v[38:39]
	v_bitop3_b32 v22, v22, 28, 48 bitop3:0xc8
	v_lshlrev_b64 v[18:19], 6, v[18:19]
	v_lshl_add_u64 v[38:39], s[28:29], 0, v[38:39]
	v_pk_mul_f32 v[28:29], v[28:29], v[36:37] op_sel_hi:[1,0]
	v_pk_mul_f32 v[26:27], v[26:27], v[36:37] op_sel_hi:[1,0]
	v_lshl_add_u64 v[18:19], s[28:29], 0, v[18:19]
	v_lshlrev_b32_e32 v22, 1, v22
	v_mov_b32_e32 v23, v1
	v_lshl_add_u64 v[38:39], v[38:39], 0, v[0:1]
	v_cvt_pk_bf16_f32 v26, v26, v27
	v_cvt_pk_bf16_f32 v27, v28, v29
	v_lshl_add_u64 v[18:19], v[18:19], 0, v[22:23]
	global_store_dwordx2 v[38:39], v[30:31], off
	global_store_dwordx2 v[38:39], v[26:27], off offset:32
	global_store_dwordx2 v[18:19], v[20:21], off
; DEVI unsigned pk2(float lo, float hi) { const f32x2_t v = {lo, hi}; const bf16x2_t b = __builtin_convertvector(v, bf16x2_t); return __builtin_bit_cast(unsigned, b); }
; DEVI size_t blk_off(int row, int col) { return ((size_t)(col >> 5) * MROWS + row) * 32 + (col & 31); }
; DEVI float xsum16(float x) { auto r = __builtin_amdgcn_permlane16_swap(__float_as_uint(x), __float_as_uint(x), false, false); return __uint_as_float(r[0]) + __uint_as_float(r[1]); }
; DEVI float xsum32(float x) { auto r = __builtin_amdgcn_permlane32_swap(__float_as_uint(x), __float_as_uint(x), false, false); return __uint_as_float(r[0]) + __uint_as_float(r[1]); }
; template <int DK, int QB, bool NA>
; DEVI void attn_item(const AttnArgs& a, unsigned char* smem) {
;     ...
;           f32x2 ls2 = {0.f, 0.f};
;           unsigned pw[2][4];
; #pragma unroll
;           for (int kb = 0; kb < 4; ++kb)
; #pragma unroll
;             for (int h = 0; h < 2; ++h) {
;               const f32x2 pe = {__builtin_amdgcn_exp2f(t[kb][h].x), __builtin_amdgcn_exp2f(t[kb][h].y)};
;               ls2 += pe;
;               pw[kb >> 1][(kb & 1) * 2 + h] = pk2(pe.x, pe.y);
;             }
;           l[qb] += ls2.x + ls2.y;
;     ...
;   if (wact) {
; #pragma unroll
;     for (int qb = 0; qb < QB; ++qb) {
;       const float lt = xsum32(xsum16(l[qb]));
;       const float inv = 1.0f / lt;
;       const int qi = w * QB * 16 + qb * 16 + l16;
;       if (qi < a.nq) {
; #pragma unroll
;         for (int db = 0; db < 4; ++db) {
;           const f32x4 v = o[db][qb] * inv;
;           *(u32x2*)(a.O + blk_off(a.orow0 + qi, a.ocol0 + db * 16 + g * 4)) = (u32x2){pk2(v[0], v[1]), pk2(v[2], v[3])};
;         }
;       }
.LBB0_2334:
	s_or_b64 exec, exec, s[0:1]
	s_nop 1
	v_add_f32_e32 v18, 0, v68
	v_add_f32_e32 v19, 0, v69
	s_mov_b64 s[8:9], s[52:53]
	v_add_f32_e32 v18, v72, v18
	v_add_f32_e32 v19, v73, v19
	s_nop 0
	v_add_f32_e32 v18, v70, v18
	v_add_f32_e32 v19, v71, v19
	s_nop 0
	v_add_f32_e32 v18, v70, v18
	v_add_f32_e32 v19, v71, v19
	s_nop 0
	v_add_f32_e32 v18, v70, v18
	v_add_f32_e32 v19, v71, v19
	s_nop 0
	v_add_f32_e32 v18, v70, v18
	v_add_f32_e32 v19, v71, v19
	s_nop 0
	v_add_f32_e32 v18, v70, v18
	v_add_f32_e32 v19, v71, v19
	s_nop 0
	v_add_f32_e32 v18, v70, v18
	v_add_f32_e32 v19, v71, v19
	s_nop 0
	v_add_f32_e32 v18, v18, v19
	v_add_f32_e32 v18, v108, v18
	v_mov_b32_e32 v19, v18
	s_nop 1
	v_permlane16_swap_b32_e32 v18, v19
	v_add_f32_e32 v19, v18, v19
	v_mov_b32_e32 v20, v19
	v_or_b32_e32 v18, 16, v35
	s_nop 0
	v_permlane32_swap_b32_e32 v19, v20
	v_cmp_gt_i32_e32 vcc, s57, v18
	s_and_saveexec_b64 s[0:1], vcc
	s_cbranch_execz .LBB0_2336
	v_add_f32_e32 v19, v19, v20
	v_div_scale_f32 v20, s[8:9], v19, v19, 1.0
	v_rcp_f32_e32 v21, v20
	v_div_scale_f32 v22, vcc, 1.0, v19, 1.0
	v_readlane_b32 s8, v251, 54
	v_fma_f32 v23, -v20, v21, 1.0
	v_fmac_f32_e32 v21, v23, v21
	v_mul_f32_e32 v23, v22, v21
	v_fma_f32 v24, -v20, v23, v22
	v_fmac_f32_e32 v23, v24, v21
	v_fma_f32 v20, -v20, v23, v22
	v_div_fmas_f32 v20, v20, v21, v23
	v_div_fixup_f32 v20, v20, v19, 1.0
	v_pk_mul_f32 v[16:17], v[16:17], v[20:21] op_sel_hi:[1,0]
	v_pk_mul_f32 v[14:15], v[14:15], v[20:21] op_sel_hi:[1,0]
	v_pk_mul_f32 v[8:9], v[8:9], v[20:21] op_sel_hi:[1,0]
	v_cvt_pk_bf16_f32 v14, v14, v15
	v_cvt_pk_bf16_f32 v15, v16, v17
	v_add_u32_e32 v16, s59, v18
	v_ashrrev_i32_e32 v17, 31, v16
	v_lshl_add_u64 v[18:19], v[16:17], 0, s[20:21]
	v_pk_mul_f32 v[6:7], v[6:7], v[20:21] op_sel_hi:[1,0]
	s_add_i32 s20, s20, 0xc280
	v_cvt_pk_bf16_f32 v6, v6, v7
	v_cvt_pk_bf16_f32 v7, v8, v9
	v_lshl_add_u64 v[8:9], v[16:17], 0, s[20:21]
	v_lshlrev_b64 v[18:19], 6, v[18:19]
	v_readlane_b32 s9, v251, 55
	v_lshlrev_b64 v[8:9], 6, v[8:9]
	v_or3_b32 v64, s56, v34, 48
	v_lshl_add_u64 v[18:19], s[8:9], 0, v[18:19]
	v_lshl_add_u64 v[8:9], s[8:9], 0, v[8:9]
	v_lshl_add_u64 v[18:19], v[18:19], 0, v[0:1]
	v_lshl_add_u64 v[8:9], v[8:9], 0, v[0:1]
	v_lshrrev_b32_e32 v0, 5, v64
	v_pk_mul_f32 v[12:13], v[12:13], v[20:21] op_sel_hi:[1,0]
	v_pk_mul_f32 v[10:11], v[10:11], v[20:21] op_sel_hi:[1,0]
	v_pk_mul_f32 v[4:5], v[4:5], v[20:21] op_sel_hi:[1,0]
	v_pk_mul_f32 v[2:3], v[2:3], v[20:21] op_sel_hi:[1,0]
	v_mul_lo_u32 v0, v0, s93
	v_cvt_pk_bf16_f32 v10, v10, v11
	v_cvt_pk_bf16_f32 v11, v12, v13
	v_cvt_pk_bf16_f32 v60, v2, v3
	v_cvt_pk_bf16_f32 v61, v4, v5
	v_lshl_add_u64 v[62:63], v[0:1], 0, v[16:17]
	s_or_b64 s[8:9], s[52:53], exec
	global_store_dwordx2 v[18:19], v[14:15], off
	global_store_dwordx2 v[18:19], v[10:11], off offset:32
	global_store_dwordx2 v[8:9], v[6:7], off
